# speedup vs baseline: 1.1255x; 1.0020x over previous
; __device__ __forceinline__ void scan_phase(const ScanArgs& s, char* shm) {
;     ...
;         if (c >= 1 && c <= NCH) {
;           const int q = c - 1;
;           const float4* sr = (const float4*)(shm + OFF_SRING + (q & 1) * (TC * 2048) + sw * 1024 + lane * 16);
;           const float* rv = (const float*)(shm + OFF_RRING + (q & 3) * (TC * 256)) + j * 4;
;           float* yb = (float*)(shm + OFF_YBUF + (q & 1) * (TC * 32));
; #pragma unroll
;           for (int u = 0; u < TC / 2; ++u) {
;             const int t = 2 * u + tp;
;             const float4 S = sr[t * 128];
;             const float4 r4 = *(const float4*)(rv + t * 64);
;             float d = (S.x * r4.x + S.y * r4.y) + (S.z * r4.z + S.w * r4.w);
;             d = row16_allreduce(d);
;             yb[t * 8 + row] = d;
;           }
.LBB0_166:
	s_andn2_b64 vcc, exec, s[68:69]
	s_cbranch_vccnz .LBB0_156
	s_add_i32 s68, s79, -1
	s_and_b32 s68, s68, 1
	s_and_b32 s69, s64, 0x3000
	v_lshl_add_u32 v10, s68, 15, v171
	v_add_u32_e32 v11, s69, v173
	v_lshl_add_u32 v12, s68, 9, v174
	v_add_u32_e32 v13, v10, v177
	v_add_u32_e32 v14, v11, v178
	v_add_u32_e32 v15, v12, v179
	ds_read_b128 v[16:19], v13 offset:0
	ds_read_b128 v[20:23], v14 offset:0
	ds_read_b128 v[24:27], v13 offset:4096
	ds_read_b128 v[28:31], v14 offset:512
	s_waitcnt lgkmcnt(2)
	v_mul_f32_e32 v17, v17, v21
	v_fmac_f32_e32 v17, v16, v20
	v_mul_f32_e32 v16, v19, v23
	v_fmac_f32_e32 v16, v18, v22
	v_add_f32_e32 v16, v17, v16
	ds_read_b128 v[32:35], v13 offset:8192
	ds_read_b128 v[36:39], v14 offset:1024
	s_waitcnt lgkmcnt(2)
	v_add_f32_dpp v16, v16, v16 quad_perm:[1,0,3,2] row_mask:0xf bank_mask:0xf bound_ctrl:1
	v_mul_f32_e32 v25, v25, v29
	v_fmac_f32_e32 v25, v24, v28
	v_add_f32_dpp v16, v16, v16 quad_perm:[2,3,0,1] row_mask:0xf bank_mask:0xf bound_ctrl:1
	v_mul_f32_e32 v24, v27, v31
	v_fmac_f32_e32 v24, v26, v30
	v_add_f32_dpp v16, v16, v16 row_half_mirror row_mask:0xf bank_mask:0xf bound_ctrl:1
	v_add_f32_e32 v24, v25, v24
	s_nop 0
	v_add_f32_dpp v16, v16, v16 row_mirror row_mask:0xf bank_mask:0xf bound_ctrl:1
	ds_write_b32 v15, v16 offset:0
	ds_read_b128 v[16:19], v13 offset:12288
	ds_read_b128 v[20:23], v14 offset:1536
	s_waitcnt lgkmcnt(3)
	v_add_f32_dpp v24, v24, v24 quad_perm:[1,0,3,2] row_mask:0xf bank_mask:0xf bound_ctrl:1
	v_mul_f32_e32 v33, v33, v37
	v_fmac_f32_e32 v33, v32, v36
	v_add_f32_dpp v24, v24, v24 quad_perm:[2,3,0,1] row_mask:0xf bank_mask:0xf bound_ctrl:1
	v_mul_f32_e32 v32, v35, v39
	v_fmac_f32_e32 v32, v34, v38
	v_add_f32_dpp v24, v24, v24 row_half_mirror row_mask:0xf bank_mask:0xf bound_ctrl:1
	v_add_f32_e32 v32, v33, v32
	s_nop 0
	v_add_f32_dpp v24, v24, v24 row_mirror row_mask:0xf bank_mask:0xf bound_ctrl:1
	ds_write_b32 v15, v24 offset:64
	ds_read_b128 v[24:27], v13 offset:16384
	ds_read_b128 v[28:31], v14 offset:2048
	s_waitcnt lgkmcnt(3)
	v_add_f32_dpp v32, v32, v32 quad_perm:[1,0,3,2] row_mask:0xf bank_mask:0xf bound_ctrl:1
	v_mul_f32_e32 v17, v17, v21
	v_fmac_f32_e32 v17, v16, v20
	v_add_f32_dpp v32, v32, v32 quad_perm:[2,3,0,1] row_mask:0xf bank_mask:0xf bound_ctrl:1
	v_mul_f32_e32 v16, v19, v23
	v_fmac_f32_e32 v16, v18, v22
	v_add_f32_dpp v32, v32, v32 row_half_mirror row_mask:0xf bank_mask:0xf bound_ctrl:1
	v_add_f32_e32 v16, v17, v16
	s_nop 0
	v_add_f32_dpp v32, v32, v32 row_mirror row_mask:0xf bank_mask:0xf bound_ctrl:1
	ds_write_b32 v15, v32 offset:128
	ds_read_b128 v[32:35], v13 offset:20480
	ds_read_b128 v[36:39], v14 offset:2560
	s_waitcnt lgkmcnt(3)
	v_add_f32_dpp v16, v16, v16 quad_perm:[1,0,3,2] row_mask:0xf bank_mask:0xf bound_ctrl:1
	v_mul_f32_e32 v25, v25, v29
	v_fmac_f32_e32 v25, v24, v28
	v_add_f32_dpp v16, v16, v16 quad_perm:[2,3,0,1] row_mask:0xf bank_mask:0xf bound_ctrl:1
	v_mul_f32_e32 v24, v27, v31
	v_fmac_f32_e32 v24, v26, v30
	v_add_f32_dpp v16, v16, v16 row_half_mirror row_mask:0xf bank_mask:0xf bound_ctrl:1
	v_add_f32_e32 v24, v25, v24
	s_nop 0
	v_add_f32_dpp v16, v16, v16 row_mirror row_mask:0xf bank_mask:0xf bound_ctrl:1
	ds_write_b32 v15, v16 offset:192
	ds_read_b128 v[16:19], v13 offset:24576
	ds_read_b128 v[20:23], v14 offset:3072
	s_waitcnt lgkmcnt(3)
	v_add_f32_dpp v24, v24, v24 quad_perm:[1,0,3,2] row_mask:0xf bank_mask:0xf bound_ctrl:1
	v_mul_f32_e32 v33, v33, v37
	v_fmac_f32_e32 v33, v32, v36
	v_add_f32_dpp v24, v24, v24 quad_perm:[2,3,0,1] row_mask:0xf bank_mask:0xf bound_ctrl:1
	v_mul_f32_e32 v32, v35, v39
	v_fmac_f32_e32 v32, v34, v38
	v_add_f32_dpp v24, v24, v24 row_half_mirror row_mask:0xf bank_mask:0xf bound_ctrl:1
	v_add_f32_e32 v32, v33, v32
	s_nop 0
	v_add_f32_dpp v24, v24, v24 row_mirror row_mask:0xf bank_mask:0xf bound_ctrl:1
	ds_write_b32 v15, v24 offset:256
	ds_read_b128 v[24:27], v13 offset:28672
	ds_read_b128 v[28:31], v14 offset:3584
	s_waitcnt lgkmcnt(3)
	v_add_f32_dpp v32, v32, v32 quad_perm:[1,0,3,2] row_mask:0xf bank_mask:0xf bound_ctrl:1
	v_mul_f32_e32 v17, v17, v21
	v_fmac_f32_e32 v17, v16, v20
	v_add_f32_dpp v32, v32, v32 quad_perm:[2,3,0,1] row_mask:0xf bank_mask:0xf bound_ctrl:1
	v_mul_f32_e32 v16, v19, v23
	v_fmac_f32_e32 v16, v18, v22
	v_add_f32_dpp v32, v32, v32 row_half_mirror row_mask:0xf bank_mask:0xf bound_ctrl:1
	v_add_f32_e32 v16, v17, v16
	s_nop 0
	v_add_f32_dpp v32, v32, v32 row_mirror row_mask:0xf bank_mask:0xf bound_ctrl:1
	ds_write_b32 v15, v32 offset:320
	s_waitcnt lgkmcnt(1)
	v_add_f32_dpp v16, v16, v16 quad_perm:[1,0,3,2] row_mask:0xf bank_mask:0xf bound_ctrl:1
	v_mul_f32_e32 v25, v25, v29
	v_fmac_f32_e32 v25, v24, v28
	v_add_f32_dpp v16, v16, v16 quad_perm:[2,3,0,1] row_mask:0xf bank_mask:0xf bound_ctrl:1
	v_mul_f32_e32 v24, v27, v31
	v_fmac_f32_e32 v24, v26, v30
	v_add_f32_dpp v16, v16, v16 row_half_mirror row_mask:0xf bank_mask:0xf bound_ctrl:1
	v_add_f32_e32 v24, v25, v24
	s_nop 0
	v_add_f32_dpp v16, v16, v16 row_mirror row_mask:0xf bank_mask:0xf bound_ctrl:1
	ds_write_b32 v15, v16 offset:384
	v_add_f32_dpp v24, v24, v24 quad_perm:[1,0,3,2] row_mask:0xf bank_mask:0xf bound_ctrl:1
	s_nop 1
	v_add_f32_dpp v24, v24, v24 quad_perm:[2,3,0,1] row_mask:0xf bank_mask:0xf bound_ctrl:1
	s_nop 1
	v_add_f32_dpp v24, v24, v24 row_half_mirror row_mask:0xf bank_mask:0xf bound_ctrl:1
	s_nop 1
	v_add_f32_dpp v24, v24, v24 row_mirror row_mask:0xf bank_mask:0xf bound_ctrl:1
	ds_write_b32 v15, v24 offset:448
	s_branch .LBB0_156

; __device__ __forceinline__ float sigmoidf_(float x) { return __builtin_amdgcn_rcpf(1.0f + __expf(-x)); }
; template <int MODE> __device__ __forceinline__ void epi_store(const GemmDesc& g, int row, int col, f32x4 v) {
;     ...
;     case E_LA: {
;       const float4 bb = *(const float4*)(g.b0 + col);
;       uint2 o; o.x = pack2(sigmoidf_(v[0] + bb.x), sigmoidf_(v[1] + bb.y)); o.y = pack2(sigmoidf_(v[2] + bb.z), sigmoidf_(v[3] + bb.w));
;       *(uint2*)((u16*)g.o0 + (size_t)row * 1024 + col) = o;
;     } break;
.LBB0_296:
	s_andn2_b64 vcc, exec, s[4:5]
	s_cbranch_vccnz .LBB0_301
	s_cmp_gt_i32 s8, 4
	s_mov_b64 s[4:5], -1
	s_cbranch_scc0 .LBB0_299
	v_or_b32_e32 v204, s38, v175
	v_lshlrev_b32_e32 v204, 2, v204
	global_load_dwordx4 v[220:223], v204, s[12:13]
	global_load_dwordx4 v[224:227], v204, s[12:13] offset:64
	global_load_dwordx4 v[228:231], v204, s[12:13] offset:128
	global_load_dwordx4 v[232:235], v204, s[12:13] offset:192
	v_and_b32_e32 v204, 63, v135
	v_and_b32_e32 v205, 15, v204
	v_lshrrev_b32_e32 v206, 4, v204
	v_lshrrev_b32_e32 v207, 3, v204
	v_and_b32_e32 v208, 7, v204
	v_lshrrev_b32_e32 v209, 8, v135
	v_bfe_u32 v210, v135, 6, 2
	v_lshrrev_b32_e32 v211, 6, v135
	v_lshlrev_b32_e32 v211, 11, v211
	v_add_u32_e32 v211, 0x20000, v211
	v_lshrrev_b32_e32 v212, 1, v206
	v_and_b32_e32 v213, 7, v205
	v_xor_b32_e32 v212, v212, v213
	v_lshlrev_b32_e32 v212, 4, v212
	v_and_b32_e32 v213, 1, v206
	v_lshl_add_u32 v212, v213, 3, v212
	v_lshl_add_u32 v212, v205, 7, v212
	v_add_u32_e32 v148, v211, v212
	v_xor_b32_e32 v149, 32, v148
	v_xor_b32_e32 v150, 64, v148
	v_xor_b32_e32 v151, 0x60, v148
	v_xor_b32_e32 v212, v208, v207
	v_lshlrev_b32_e32 v212, 4, v212
	v_lshl_add_u32 v212, v207, 7, v212
	v_add_u32_e32 v156, v211, v212
	v_lshl_add_u32 v212, v209, 7, v207
	v_add_u32_e32 v212, s39, v212
	v_lshlrev_b32_e32 v213, 3, v208
	v_lshl_add_u32 v213, v210, 6, v213
	v_add_u32_e32 v213, s38, v213
	v_lshlrev_b32_e32 v212, 10, v212
	v_add_lshl_u32 v146, v212, v213, 1
	v_add_u32_e32 v147, 0x4000, v146
	s_waitcnt vmcnt(0)
	v_pk_add_f32 v[204:205], v[124:125], v[220:221]
	v_pk_add_f32 v[206:207], v[126:127], v[222:223]
	v_mul_f32_e32 v204, 0xbfb8aa3b, v204
	v_mul_f32_e32 v205, 0xbfb8aa3b, v205
	v_mul_f32_e32 v206, 0xbfb8aa3b, v206
	v_mul_f32_e32 v207, 0xbfb8aa3b, v207
	v_exp_f32_e32 v204, v204
	v_exp_f32_e32 v205, v205
	v_exp_f32_e32 v206, v206
	v_exp_f32_e32 v207, v207
	v_add_f32_e32 v204, 1.0, v204
	v_add_f32_e32 v205, 1.0, v205
	v_add_f32_e32 v206, 1.0, v206
	v_add_f32_e32 v207, 1.0, v207
	v_rcp_f32_e32 v204, v204
	v_rcp_f32_e32 v205, v205
	v_rcp_f32_e32 v206, v206
	v_rcp_f32_e32 v207, v207
	v_cvt_pk_bf16_f32 v152, v204, v205
	v_cvt_pk_bf16_f32 v153, v206, v207
	ds_write_b64 v148, v[152:153]
	v_pk_add_f32 v[212:213], v[120:121], v[224:225]
	v_pk_add_f32 v[214:215], v[122:123], v[226:227]
	v_mul_f32_e32 v212, 0xbfb8aa3b, v212
	v_mul_f32_e32 v213, 0xbfb8aa3b, v213
	v_mul_f32_e32 v214, 0xbfb8aa3b, v214
	v_mul_f32_e32 v215, 0xbfb8aa3b, v215
	v_exp_f32_e32 v212, v212
	v_exp_f32_e32 v213, v213
	v_exp_f32_e32 v214, v214
	v_exp_f32_e32 v215, v215
	v_add_f32_e32 v212, 1.0, v212
	v_add_f32_e32 v213, 1.0, v213
	v_add_f32_e32 v214, 1.0, v214
	v_add_f32_e32 v215, 1.0, v215
	v_rcp_f32_e32 v212, v212
	v_rcp_f32_e32 v213, v213
	v_rcp_f32_e32 v214, v214
	v_rcp_f32_e32 v215, v215
	v_cvt_pk_bf16_f32 v154, v212, v213
	v_cvt_pk_bf16_f32 v155, v214, v215
	ds_write_b64 v149, v[154:155]
	v_pk_add_f32 v[204:205], v[116:117], v[228:229]
	v_pk_add_f32 v[206:207], v[118:119], v[230:231]
	v_mul_f32_e32 v204, 0xbfb8aa3b, v204
	v_mul_f32_e32 v205, 0xbfb8aa3b, v205
	v_mul_f32_e32 v206, 0xbfb8aa3b, v206
	v_mul_f32_e32 v207, 0xbfb8aa3b, v207
	v_exp_f32_e32 v204, v204
	v_exp_f32_e32 v205, v205
	v_exp_f32_e32 v206, v206
	v_exp_f32_e32 v207, v207
	v_add_f32_e32 v204, 1.0, v204
	v_add_f32_e32 v205, 1.0, v205
	v_add_f32_e32 v206, 1.0, v206
	v_add_f32_e32 v207, 1.0, v207
	v_rcp_f32_e32 v204, v204
	v_rcp_f32_e32 v205, v205
	v_rcp_f32_e32 v206, v206
	v_rcp_f32_e32 v207, v207
	v_cvt_pk_bf16_f32 v152, v204, v205
	v_cvt_pk_bf16_f32 v153, v206, v207
	ds_write_b64 v150, v[152:153]
	v_pk_add_f32 v[212:213], v[112:113], v[232:233]
	v_pk_add_f32 v[214:215], v[114:115], v[234:235]
	v_mul_f32_e32 v212, 0xbfb8aa3b, v212
	v_mul_f32_e32 v213, 0xbfb8aa3b, v213
	v_mul_f32_e32 v214, 0xbfb8aa3b, v214
	v_mul_f32_e32 v215, 0xbfb8aa3b, v215
	v_exp_f32_e32 v212, v212
	v_exp_f32_e32 v213, v213
	v_exp_f32_e32 v214, v214
	v_exp_f32_e32 v215, v215
	v_add_f32_e32 v212, 1.0, v212
	v_add_f32_e32 v213, 1.0, v213
	v_add_f32_e32 v214, 1.0, v214
	v_add_f32_e32 v215, 1.0, v215
	v_rcp_f32_e32 v212, v212
	v_rcp_f32_e32 v213, v213
	v_rcp_f32_e32 v214, v214
	v_rcp_f32_e32 v215, v215
	v_cvt_pk_bf16_f32 v154, v212, v213
	v_cvt_pk_bf16_f32 v155, v214, v215
	ds_write_b64 v151, v[154:155]
	ds_read_b128 v[236:239], v156
	ds_read_b128 v[240:243], v156 offset:1024
	v_pk_add_f32 v[204:205], v[108:109], v[220:221]
	v_pk_add_f32 v[206:207], v[110:111], v[222:223]
	v_mul_f32_e32 v204, 0xbfb8aa3b, v204
	v_mul_f32_e32 v205, 0xbfb8aa3b, v205
	v_mul_f32_e32 v206, 0xbfb8aa3b, v206
	v_mul_f32_e32 v207, 0xbfb8aa3b, v207
	v_exp_f32_e32 v204, v204
	v_exp_f32_e32 v205, v205
	v_exp_f32_e32 v206, v206
	v_exp_f32_e32 v207, v207
	v_add_f32_e32 v204, 1.0, v204
	v_add_f32_e32 v205, 1.0, v205
	v_add_f32_e32 v206, 1.0, v206
	v_add_f32_e32 v207, 1.0, v207
	v_rcp_f32_e32 v204, v204
	v_rcp_f32_e32 v205, v205
	v_rcp_f32_e32 v206, v206
	v_rcp_f32_e32 v207, v207
	v_cvt_pk_bf16_f32 v152, v204, v205
	v_cvt_pk_bf16_f32 v153, v206, v207
	ds_write_b64 v148, v[152:153]
	v_pk_add_f32 v[212:213], v[104:105], v[224:225]
	v_pk_add_f32 v[214:215], v[106:107], v[226:227]
	v_mul_f32_e32 v212, 0xbfb8aa3b, v212
	v_mul_f32_e32 v213, 0xbfb8aa3b, v213
	v_mul_f32_e32 v214, 0xbfb8aa3b, v214
	v_mul_f32_e32 v215, 0xbfb8aa3b, v215
	v_exp_f32_e32 v212, v212
	v_exp_f32_e32 v213, v213
	v_exp_f32_e32 v214, v214
	v_exp_f32_e32 v215, v215
	v_add_f32_e32 v212, 1.0, v212
	v_add_f32_e32 v213, 1.0, v213
	v_add_f32_e32 v214, 1.0, v214
	v_add_f32_e32 v215, 1.0, v215
	v_rcp_f32_e32 v212, v212
	v_rcp_f32_e32 v213, v213
	v_rcp_f32_e32 v214, v214
	v_rcp_f32_e32 v215, v215
	v_cvt_pk_bf16_f32 v154, v212, v213
; __device__ __forceinline__ float sigmoidf_(float x) { return __builtin_amdgcn_rcpf(1.0f + __expf(-x)); }
; template <int MODE> __device__ __forceinline__ void epi_store(const GemmDesc& g, int row, int col, f32x4 v) {
;     ...
;     case E_LA: {
;       const float4 bb = *(const float4*)(g.b0 + col);
;       uint2 o; o.x = pack2(sigmoidf_(v[0] + bb.x), sigmoidf_(v[1] + bb.y)); o.y = pack2(sigmoidf_(v[2] + bb.z), sigmoidf_(v[3] + bb.w));
;       *(uint2*)((u16*)g.o0 + (size_t)row * 1024 + col) = o;
;     } break;
	v_cvt_pk_bf16_f32 v155, v214, v215
	ds_write_b64 v149, v[154:155]
	v_pk_add_f32 v[204:205], v[100:101], v[228:229]
	v_pk_add_f32 v[206:207], v[102:103], v[230:231]
	v_mul_f32_e32 v204, 0xbfb8aa3b, v204
	v_mul_f32_e32 v205, 0xbfb8aa3b, v205
	v_mul_f32_e32 v206, 0xbfb8aa3b, v206
	v_mul_f32_e32 v207, 0xbfb8aa3b, v207
	v_exp_f32_e32 v204, v204
	v_exp_f32_e32 v205, v205
	v_exp_f32_e32 v206, v206
	v_exp_f32_e32 v207, v207
	v_add_f32_e32 v204, 1.0, v204
	v_add_f32_e32 v205, 1.0, v205
	v_add_f32_e32 v206, 1.0, v206
	v_add_f32_e32 v207, 1.0, v207
	v_rcp_f32_e32 v204, v204
	v_rcp_f32_e32 v205, v205
	v_rcp_f32_e32 v206, v206
	v_rcp_f32_e32 v207, v207
	v_cvt_pk_bf16_f32 v152, v204, v205
	v_cvt_pk_bf16_f32 v153, v206, v207
	ds_write_b64 v150, v[152:153]
	v_pk_add_f32 v[212:213], v[96:97], v[232:233]
	v_pk_add_f32 v[214:215], v[98:99], v[234:235]
	v_mul_f32_e32 v212, 0xbfb8aa3b, v212
	v_mul_f32_e32 v213, 0xbfb8aa3b, v213
	v_mul_f32_e32 v214, 0xbfb8aa3b, v214
	v_mul_f32_e32 v215, 0xbfb8aa3b, v215
	v_exp_f32_e32 v212, v212
	v_exp_f32_e32 v213, v213
	v_exp_f32_e32 v214, v214
	v_exp_f32_e32 v215, v215
	v_add_f32_e32 v212, 1.0, v212
	v_add_f32_e32 v213, 1.0, v213
	v_add_f32_e32 v214, 1.0, v214
	v_add_f32_e32 v215, 1.0, v215
	v_rcp_f32_e32 v212, v212
	v_rcp_f32_e32 v213, v213
	v_rcp_f32_e32 v214, v214
	v_rcp_f32_e32 v215, v215
	v_cvt_pk_bf16_f32 v154, v212, v213
	v_cvt_pk_bf16_f32 v155, v214, v215
	ds_write_b64 v151, v[154:155]
	s_waitcnt lgkmcnt(4)
	global_store_dwordx4 v146, v[236:239], s[66:67]
	global_store_dwordx4 v147, v[240:243], s[66:67]
	v_add_u32_e32 v146, 0x8000, v146
	v_add_u32_e32 v147, 0x8000, v147
	ds_read_b128 v[236:239], v156
	ds_read_b128 v[240:243], v156 offset:1024
	v_pk_add_f32 v[204:205], v[92:93], v[220:221]
	v_pk_add_f32 v[206:207], v[94:95], v[222:223]
	v_mul_f32_e32 v204, 0xbfb8aa3b, v204
	v_mul_f32_e32 v205, 0xbfb8aa3b, v205
	v_mul_f32_e32 v206, 0xbfb8aa3b, v206
	v_mul_f32_e32 v207, 0xbfb8aa3b, v207
	v_exp_f32_e32 v204, v204
	v_exp_f32_e32 v205, v205
	v_exp_f32_e32 v206, v206
	v_exp_f32_e32 v207, v207
	v_add_f32_e32 v204, 1.0, v204
	v_add_f32_e32 v205, 1.0, v205
	v_add_f32_e32 v206, 1.0, v206
	v_add_f32_e32 v207, 1.0, v207
	v_rcp_f32_e32 v204, v204
	v_rcp_f32_e32 v205, v205
	v_rcp_f32_e32 v206, v206
	v_rcp_f32_e32 v207, v207
	v_cvt_pk_bf16_f32 v152, v204, v205
	v_cvt_pk_bf16_f32 v153, v206, v207
	ds_write_b64 v148, v[152:153]
	v_pk_add_f32 v[212:213], v[88:89], v[224:225]
	v_pk_add_f32 v[214:215], v[90:91], v[226:227]
	v_mul_f32_e32 v212, 0xbfb8aa3b, v212
	v_mul_f32_e32 v213, 0xbfb8aa3b, v213
	v_mul_f32_e32 v214, 0xbfb8aa3b, v214
	v_mul_f32_e32 v215, 0xbfb8aa3b, v215
	v_exp_f32_e32 v212, v212
	v_exp_f32_e32 v213, v213
	v_exp_f32_e32 v214, v214
	v_exp_f32_e32 v215, v215
	v_add_f32_e32 v212, 1.0, v212
	v_add_f32_e32 v213, 1.0, v213
	v_add_f32_e32 v214, 1.0, v214
	v_add_f32_e32 v215, 1.0, v215
	v_rcp_f32_e32 v212, v212
	v_rcp_f32_e32 v213, v213
	v_rcp_f32_e32 v214, v214
	v_rcp_f32_e32 v215, v215
	v_cvt_pk_bf16_f32 v154, v212, v213
	v_cvt_pk_bf16_f32 v155, v214, v215
	ds_write_b64 v149, v[154:155]
	v_pk_add_f32 v[204:205], v[84:85], v[228:229]
	v_pk_add_f32 v[206:207], v[86:87], v[230:231]
	v_mul_f32_e32 v204, 0xbfb8aa3b, v204
	v_mul_f32_e32 v205, 0xbfb8aa3b, v205
	v_mul_f32_e32 v206, 0xbfb8aa3b, v206
	v_mul_f32_e32 v207, 0xbfb8aa3b, v207
	v_exp_f32_e32 v204, v204
	v_exp_f32_e32 v205, v205
	v_exp_f32_e32 v206, v206
	v_exp_f32_e32 v207, v207
	v_add_f32_e32 v204, 1.0, v204
	v_add_f32_e32 v205, 1.0, v205
	v_add_f32_e32 v206, 1.0, v206
	v_add_f32_e32 v207, 1.0, v207
	v_rcp_f32_e32 v204, v204
	v_rcp_f32_e32 v205, v205
	v_rcp_f32_e32 v206, v206
	v_rcp_f32_e32 v207, v207
	v_cvt_pk_bf16_f32 v152, v204, v205
	v_cvt_pk_bf16_f32 v153, v206, v207
	ds_write_b64 v150, v[152:153]
	v_pk_add_f32 v[212:213], v[80:81], v[232:233]
	v_pk_add_f32 v[214:215], v[82:83], v[234:235]
	v_mul_f32_e32 v212, 0xbfb8aa3b, v212
	v_mul_f32_e32 v213, 0xbfb8aa3b, v213
	v_mul_f32_e32 v214, 0xbfb8aa3b, v214
	v_mul_f32_e32 v215, 0xbfb8aa3b, v215
	v_exp_f32_e32 v212, v212
	v_exp_f32_e32 v213, v213
	v_exp_f32_e32 v214, v214
	v_exp_f32_e32 v215, v215
	v_add_f32_e32 v212, 1.0, v212
	v_add_f32_e32 v213, 1.0, v213
	v_add_f32_e32 v214, 1.0, v214
	v_add_f32_e32 v215, 1.0, v215
	v_rcp_f32_e32 v212, v212
	v_rcp_f32_e32 v213, v213
	v_rcp_f32_e32 v214, v214
	v_rcp_f32_e32 v215, v215
	v_cvt_pk_bf16_f32 v154, v212, v213
	v_cvt_pk_bf16_f32 v155, v214, v215
	ds_write_b64 v151, v[154:155]
	s_waitcnt lgkmcnt(4)
; __device__ __forceinline__ float sigmoidf_(float x) { return __builtin_amdgcn_rcpf(1.0f + __expf(-x)); }
; template <int MODE> __device__ __forceinline__ void epi_store(const GemmDesc& g, int row, int col, f32x4 v) {
;     ...
;     case E_LA: {
;       const float4 bb = *(const float4*)(g.b0 + col);
;       uint2 o; o.x = pack2(sigmoidf_(v[0] + bb.x), sigmoidf_(v[1] + bb.y)); o.y = pack2(sigmoidf_(v[2] + bb.z), sigmoidf_(v[3] + bb.w));
;       *(uint2*)((u16*)g.o0 + (size_t)row * 1024 + col) = o;
;     } break;
	global_store_dwordx4 v146, v[236:239], s[66:67]
	global_store_dwordx4 v147, v[240:243], s[66:67]
	v_add_u32_e32 v146, 0x8000, v146
	v_add_u32_e32 v147, 0x8000, v147
	ds_read_b128 v[236:239], v156
	ds_read_b128 v[240:243], v156 offset:1024
	v_pk_add_f32 v[204:205], v[76:77], v[220:221]
	v_pk_add_f32 v[206:207], v[78:79], v[222:223]
	v_mul_f32_e32 v204, 0xbfb8aa3b, v204
	v_mul_f32_e32 v205, 0xbfb8aa3b, v205
	v_mul_f32_e32 v206, 0xbfb8aa3b, v206
	v_mul_f32_e32 v207, 0xbfb8aa3b, v207
	v_exp_f32_e32 v204, v204
	v_exp_f32_e32 v205, v205
	v_exp_f32_e32 v206, v206
	v_exp_f32_e32 v207, v207
	v_add_f32_e32 v204, 1.0, v204
	v_add_f32_e32 v205, 1.0, v205
	v_add_f32_e32 v206, 1.0, v206
	v_add_f32_e32 v207, 1.0, v207
	v_rcp_f32_e32 v204, v204
	v_rcp_f32_e32 v205, v205
	v_rcp_f32_e32 v206, v206
	v_rcp_f32_e32 v207, v207
	v_cvt_pk_bf16_f32 v152, v204, v205
	v_cvt_pk_bf16_f32 v153, v206, v207
	ds_write_b64 v148, v[152:153]
	v_pk_add_f32 v[212:213], v[72:73], v[224:225]
	v_pk_add_f32 v[214:215], v[74:75], v[226:227]
	v_mul_f32_e32 v212, 0xbfb8aa3b, v212
	v_mul_f32_e32 v213, 0xbfb8aa3b, v213
	v_mul_f32_e32 v214, 0xbfb8aa3b, v214
	v_mul_f32_e32 v215, 0xbfb8aa3b, v215
	v_exp_f32_e32 v212, v212
	v_exp_f32_e32 v213, v213
	v_exp_f32_e32 v214, v214
	v_exp_f32_e32 v215, v215
	v_add_f32_e32 v212, 1.0, v212
	v_add_f32_e32 v213, 1.0, v213
	v_add_f32_e32 v214, 1.0, v214
	v_add_f32_e32 v215, 1.0, v215
	v_rcp_f32_e32 v212, v212
	v_rcp_f32_e32 v213, v213
	v_rcp_f32_e32 v214, v214
	v_rcp_f32_e32 v215, v215
	v_cvt_pk_bf16_f32 v154, v212, v213
	v_cvt_pk_bf16_f32 v155, v214, v215
	ds_write_b64 v149, v[154:155]
	v_pk_add_f32 v[204:205], v[68:69], v[228:229]
	v_pk_add_f32 v[206:207], v[70:71], v[230:231]
	v_mul_f32_e32 v204, 0xbfb8aa3b, v204
	v_mul_f32_e32 v205, 0xbfb8aa3b, v205
	v_mul_f32_e32 v206, 0xbfb8aa3b, v206
	v_mul_f32_e32 v207, 0xbfb8aa3b, v207
	v_exp_f32_e32 v204, v204
	v_exp_f32_e32 v205, v205
	v_exp_f32_e32 v206, v206
	v_exp_f32_e32 v207, v207
	v_add_f32_e32 v204, 1.0, v204
	v_add_f32_e32 v205, 1.0, v205
	v_add_f32_e32 v206, 1.0, v206
	v_add_f32_e32 v207, 1.0, v207
	v_rcp_f32_e32 v204, v204
	v_rcp_f32_e32 v205, v205
	v_rcp_f32_e32 v206, v206
	v_rcp_f32_e32 v207, v207
	v_cvt_pk_bf16_f32 v152, v204, v205
	v_cvt_pk_bf16_f32 v153, v206, v207
	ds_write_b64 v150, v[152:153]
	v_pk_add_f32 v[212:213], v[64:65], v[232:233]
	v_pk_add_f32 v[214:215], v[66:67], v[234:235]
	v_mul_f32_e32 v212, 0xbfb8aa3b, v212
	v_mul_f32_e32 v213, 0xbfb8aa3b, v213
	v_mul_f32_e32 v214, 0xbfb8aa3b, v214
	v_mul_f32_e32 v215, 0xbfb8aa3b, v215
	v_exp_f32_e32 v212, v212
	v_exp_f32_e32 v213, v213
	v_exp_f32_e32 v214, v214
	v_exp_f32_e32 v215, v215
	v_add_f32_e32 v212, 1.0, v212
	v_add_f32_e32 v213, 1.0, v213
	v_add_f32_e32 v214, 1.0, v214
	v_add_f32_e32 v215, 1.0, v215
	v_rcp_f32_e32 v212, v212
	v_rcp_f32_e32 v213, v213
	v_rcp_f32_e32 v214, v214
	v_rcp_f32_e32 v215, v215
	v_cvt_pk_bf16_f32 v154, v212, v213
	v_cvt_pk_bf16_f32 v155, v214, v215
	ds_write_b64 v151, v[154:155]
	s_waitcnt lgkmcnt(4)
	global_store_dwordx4 v146, v[236:239], s[66:67]
	global_store_dwordx4 v147, v[240:243], s[66:67]
	v_add_u32_e32 v146, 0x8000, v146
	v_add_u32_e32 v147, 0x8000, v147
	ds_read_b128 v[236:239], v156
	ds_read_b128 v[240:243], v156 offset:1024
	v_pk_add_f32 v[204:205], v[60:61], v[220:221]
	v_pk_add_f32 v[206:207], v[62:63], v[222:223]
	v_mul_f32_e32 v204, 0xbfb8aa3b, v204
	v_mul_f32_e32 v205, 0xbfb8aa3b, v205
	v_mul_f32_e32 v206, 0xbfb8aa3b, v206
	v_mul_f32_e32 v207, 0xbfb8aa3b, v207
	v_exp_f32_e32 v204, v204
	v_exp_f32_e32 v205, v205
	v_exp_f32_e32 v206, v206
	v_exp_f32_e32 v207, v207
	v_add_f32_e32 v204, 1.0, v204
	v_add_f32_e32 v205, 1.0, v205
	v_add_f32_e32 v206, 1.0, v206
	v_add_f32_e32 v207, 1.0, v207
	v_rcp_f32_e32 v204, v204
	v_rcp_f32_e32 v205, v205
	v_rcp_f32_e32 v206, v206
	v_rcp_f32_e32 v207, v207
	v_cvt_pk_bf16_f32 v152, v204, v205
	v_cvt_pk_bf16_f32 v153, v206, v207
	ds_write_b64 v148, v[152:153]
	v_pk_add_f32 v[212:213], v[56:57], v[224:225]
	v_pk_add_f32 v[214:215], v[58:59], v[226:227]
	v_mul_f32_e32 v212, 0xbfb8aa3b, v212
	v_mul_f32_e32 v213, 0xbfb8aa3b, v213
	v_mul_f32_e32 v214, 0xbfb8aa3b, v214
	v_mul_f32_e32 v215, 0xbfb8aa3b, v215
	v_exp_f32_e32 v212, v212
	v_exp_f32_e32 v213, v213
	v_exp_f32_e32 v214, v214
	v_exp_f32_e32 v215, v215
	v_add_f32_e32 v212, 1.0, v212
	v_add_f32_e32 v213, 1.0, v213
	v_add_f32_e32 v214, 1.0, v214
	v_add_f32_e32 v215, 1.0, v215
	v_rcp_f32_e32 v212, v212
	v_rcp_f32_e32 v213, v213
	v_rcp_f32_e32 v214, v214
	v_rcp_f32_e32 v215, v215
	v_cvt_pk_bf16_f32 v154, v212, v213
	v_cvt_pk_bf16_f32 v155, v214, v215
	ds_write_b64 v149, v[154:155]
	v_pk_add_f32 v[204:205], v[52:53], v[228:229]
	v_pk_add_f32 v[206:207], v[54:55], v[230:231]
	v_mul_f32_e32 v204, 0xbfb8aa3b, v204
	v_mul_f32_e32 v205, 0xbfb8aa3b, v205
	v_mul_f32_e32 v206, 0xbfb8aa3b, v206
	v_mul_f32_e32 v207, 0xbfb8aa3b, v207
	v_exp_f32_e32 v204, v204
	v_exp_f32_e32 v205, v205
	v_exp_f32_e32 v206, v206
	v_exp_f32_e32 v207, v207
	v_add_f32_e32 v204, 1.0, v204
	v_add_f32_e32 v205, 1.0, v205
	v_add_f32_e32 v206, 1.0, v206
	v_add_f32_e32 v207, 1.0, v207
	v_rcp_f32_e32 v204, v204
	v_rcp_f32_e32 v205, v205
	v_rcp_f32_e32 v206, v206
	v_rcp_f32_e32 v207, v207
	v_cvt_pk_bf16_f32 v152, v204, v205
	v_cvt_pk_bf16_f32 v153, v206, v207
	ds_write_b64 v150, v[152:153]
	v_pk_add_f32 v[212:213], v[48:49], v[232:233]
	v_pk_add_f32 v[214:215], v[50:51], v[234:235]
	v_mul_f32_e32 v212, 0xbfb8aa3b, v212
	v_mul_f32_e32 v213, 0xbfb8aa3b, v213
	v_mul_f32_e32 v214, 0xbfb8aa3b, v214
	v_mul_f32_e32 v215, 0xbfb8aa3b, v215
	v_exp_f32_e32 v212, v212
	v_exp_f32_e32 v213, v213
	v_exp_f32_e32 v214, v214
	v_exp_f32_e32 v215, v215
	v_add_f32_e32 v212, 1.0, v212
	v_add_f32_e32 v213, 1.0, v213
	v_add_f32_e32 v214, 1.0, v214
	v_add_f32_e32 v215, 1.0, v215
	v_rcp_f32_e32 v212, v212
	v_rcp_f32_e32 v213, v213
	v_rcp_f32_e32 v214, v214
	v_rcp_f32_e32 v215, v215
	v_cvt_pk_bf16_f32 v154, v212, v213
	v_cvt_pk_bf16_f32 v155, v214, v215
	ds_write_b64 v151, v[154:155]
	s_waitcnt lgkmcnt(4)
; __device__ __forceinline__ float sigmoidf_(float x) { return __builtin_amdgcn_rcpf(1.0f + __expf(-x)); }
; template <int MODE> __device__ __forceinline__ void epi_store(const GemmDesc& g, int row, int col, f32x4 v) {
;     ...
;     case E_LA: {
;       const float4 bb = *(const float4*)(g.b0 + col);
;       uint2 o; o.x = pack2(sigmoidf_(v[0] + bb.x), sigmoidf_(v[1] + bb.y)); o.y = pack2(sigmoidf_(v[2] + bb.z), sigmoidf_(v[3] + bb.w));
;       *(uint2*)((u16*)g.o0 + (size_t)row * 1024 + col) = o;
;     } break;
	global_store_dwordx4 v146, v[236:239], s[66:67]
	global_store_dwordx4 v147, v[240:243], s[66:67]
	v_add_u32_e32 v146, 0x8000, v146
	v_add_u32_e32 v147, 0x8000, v147
	ds_read_b128 v[236:239], v156
	ds_read_b128 v[240:243], v156 offset:1024
	v_pk_add_f32 v[204:205], v[44:45], v[220:221]
	v_pk_add_f32 v[206:207], v[46:47], v[222:223]
	v_mul_f32_e32 v204, 0xbfb8aa3b, v204
	v_mul_f32_e32 v205, 0xbfb8aa3b, v205
	v_mul_f32_e32 v206, 0xbfb8aa3b, v206
	v_mul_f32_e32 v207, 0xbfb8aa3b, v207
	v_exp_f32_e32 v204, v204
	v_exp_f32_e32 v205, v205
	v_exp_f32_e32 v206, v206
	v_exp_f32_e32 v207, v207
	v_add_f32_e32 v204, 1.0, v204
	v_add_f32_e32 v205, 1.0, v205
	v_add_f32_e32 v206, 1.0, v206
	v_add_f32_e32 v207, 1.0, v207
	v_rcp_f32_e32 v204, v204
	v_rcp_f32_e32 v205, v205
	v_rcp_f32_e32 v206, v206
	v_rcp_f32_e32 v207, v207
	v_cvt_pk_bf16_f32 v152, v204, v205
	v_cvt_pk_bf16_f32 v153, v206, v207
	ds_write_b64 v148, v[152:153]
	v_pk_add_f32 v[212:213], v[40:41], v[224:225]
	v_pk_add_f32 v[214:215], v[42:43], v[226:227]
	v_mul_f32_e32 v212, 0xbfb8aa3b, v212
	v_mul_f32_e32 v213, 0xbfb8aa3b, v213
	v_mul_f32_e32 v214, 0xbfb8aa3b, v214
	v_mul_f32_e32 v215, 0xbfb8aa3b, v215
	v_exp_f32_e32 v212, v212
	v_exp_f32_e32 v213, v213
	v_exp_f32_e32 v214, v214
	v_exp_f32_e32 v215, v215
	v_add_f32_e32 v212, 1.0, v212
	v_add_f32_e32 v213, 1.0, v213
	v_add_f32_e32 v214, 1.0, v214
	v_add_f32_e32 v215, 1.0, v215
	v_rcp_f32_e32 v212, v212
	v_rcp_f32_e32 v213, v213
	v_rcp_f32_e32 v214, v214
	v_rcp_f32_e32 v215, v215
	v_cvt_pk_bf16_f32 v154, v212, v213
	v_cvt_pk_bf16_f32 v155, v214, v215
	ds_write_b64 v149, v[154:155]
	v_pk_add_f32 v[204:205], v[36:37], v[228:229]
	v_pk_add_f32 v[206:207], v[38:39], v[230:231]
	v_mul_f32_e32 v204, 0xbfb8aa3b, v204
	v_mul_f32_e32 v205, 0xbfb8aa3b, v205
	v_mul_f32_e32 v206, 0xbfb8aa3b, v206
	v_mul_f32_e32 v207, 0xbfb8aa3b, v207
	v_exp_f32_e32 v204, v204
	v_exp_f32_e32 v205, v205
	v_exp_f32_e32 v206, v206
	v_exp_f32_e32 v207, v207
	v_add_f32_e32 v204, 1.0, v204
	v_add_f32_e32 v205, 1.0, v205
	v_add_f32_e32 v206, 1.0, v206
	v_add_f32_e32 v207, 1.0, v207
	v_rcp_f32_e32 v204, v204
	v_rcp_f32_e32 v205, v205
	v_rcp_f32_e32 v206, v206
	v_rcp_f32_e32 v207, v207
	v_cvt_pk_bf16_f32 v152, v204, v205
	v_cvt_pk_bf16_f32 v153, v206, v207
	ds_write_b64 v150, v[152:153]
	v_pk_add_f32 v[212:213], v[32:33], v[232:233]
	v_pk_add_f32 v[214:215], v[34:35], v[234:235]
	v_mul_f32_e32 v212, 0xbfb8aa3b, v212
	v_mul_f32_e32 v213, 0xbfb8aa3b, v213
	v_mul_f32_e32 v214, 0xbfb8aa3b, v214
	v_mul_f32_e32 v215, 0xbfb8aa3b, v215
	v_exp_f32_e32 v212, v212
	v_exp_f32_e32 v213, v213
	v_exp_f32_e32 v214, v214
	v_exp_f32_e32 v215, v215
	v_add_f32_e32 v212, 1.0, v212
	v_add_f32_e32 v213, 1.0, v213
	v_add_f32_e32 v214, 1.0, v214
	v_add_f32_e32 v215, 1.0, v215
	v_rcp_f32_e32 v212, v212
	v_rcp_f32_e32 v213, v213
	v_rcp_f32_e32 v214, v214
	v_rcp_f32_e32 v215, v215
	v_cvt_pk_bf16_f32 v154, v212, v213
	v_cvt_pk_bf16_f32 v155, v214, v215
	ds_write_b64 v151, v[154:155]
	s_waitcnt lgkmcnt(4)
	global_store_dwordx4 v146, v[236:239], s[66:67]
	global_store_dwordx4 v147, v[240:243], s[66:67]
	v_add_u32_e32 v146, 0x8000, v146
	v_add_u32_e32 v147, 0x8000, v147
	ds_read_b128 v[236:239], v156
	ds_read_b128 v[240:243], v156 offset:1024
	v_pk_add_f32 v[204:205], v[28:29], v[220:221]
	v_pk_add_f32 v[206:207], v[30:31], v[222:223]
	v_mul_f32_e32 v204, 0xbfb8aa3b, v204
	v_mul_f32_e32 v205, 0xbfb8aa3b, v205
	v_mul_f32_e32 v206, 0xbfb8aa3b, v206
	v_mul_f32_e32 v207, 0xbfb8aa3b, v207
	v_exp_f32_e32 v204, v204
	v_exp_f32_e32 v205, v205
	v_exp_f32_e32 v206, v206
	v_exp_f32_e32 v207, v207
	v_add_f32_e32 v204, 1.0, v204
	v_add_f32_e32 v205, 1.0, v205
	v_add_f32_e32 v206, 1.0, v206
	v_add_f32_e32 v207, 1.0, v207
	v_rcp_f32_e32 v204, v204
	v_rcp_f32_e32 v205, v205
	v_rcp_f32_e32 v206, v206
	v_rcp_f32_e32 v207, v207
	v_cvt_pk_bf16_f32 v152, v204, v205
	v_cvt_pk_bf16_f32 v153, v206, v207
	ds_write_b64 v148, v[152:153]
	v_pk_add_f32 v[212:213], v[24:25], v[224:225]
	v_pk_add_f32 v[214:215], v[26:27], v[226:227]
	v_mul_f32_e32 v212, 0xbfb8aa3b, v212
	v_mul_f32_e32 v213, 0xbfb8aa3b, v213
	v_mul_f32_e32 v214, 0xbfb8aa3b, v214
	v_mul_f32_e32 v215, 0xbfb8aa3b, v215
	v_exp_f32_e32 v212, v212
	v_exp_f32_e32 v213, v213
	v_exp_f32_e32 v214, v214
	v_exp_f32_e32 v215, v215
	v_add_f32_e32 v212, 1.0, v212
	v_add_f32_e32 v213, 1.0, v213
	v_add_f32_e32 v214, 1.0, v214
	v_add_f32_e32 v215, 1.0, v215
	v_rcp_f32_e32 v212, v212
	v_rcp_f32_e32 v213, v213
	v_rcp_f32_e32 v214, v214
	v_rcp_f32_e32 v215, v215
	v_cvt_pk_bf16_f32 v154, v212, v213
	v_cvt_pk_bf16_f32 v155, v214, v215
	ds_write_b64 v149, v[154:155]
	v_pk_add_f32 v[204:205], v[20:21], v[228:229]
	v_pk_add_f32 v[206:207], v[22:23], v[230:231]
	v_mul_f32_e32 v204, 0xbfb8aa3b, v204
	v_mul_f32_e32 v205, 0xbfb8aa3b, v205
	v_mul_f32_e32 v206, 0xbfb8aa3b, v206
	v_mul_f32_e32 v207, 0xbfb8aa3b, v207
	v_exp_f32_e32 v204, v204
	v_exp_f32_e32 v205, v205
	v_exp_f32_e32 v206, v206
	v_exp_f32_e32 v207, v207
	v_add_f32_e32 v204, 1.0, v204
	v_add_f32_e32 v205, 1.0, v205
	v_add_f32_e32 v206, 1.0, v206
	v_add_f32_e32 v207, 1.0, v207
	v_rcp_f32_e32 v204, v204
	v_rcp_f32_e32 v205, v205
	v_rcp_f32_e32 v206, v206
	v_rcp_f32_e32 v207, v207
	v_cvt_pk_bf16_f32 v152, v204, v205
	v_cvt_pk_bf16_f32 v153, v206, v207
	ds_write_b64 v150, v[152:153]
	v_pk_add_f32 v[212:213], v[16:17], v[232:233]
	v_pk_add_f32 v[214:215], v[18:19], v[234:235]
	v_mul_f32_e32 v212, 0xbfb8aa3b, v212
	v_mul_f32_e32 v213, 0xbfb8aa3b, v213
	v_mul_f32_e32 v214, 0xbfb8aa3b, v214
	v_mul_f32_e32 v215, 0xbfb8aa3b, v215
	v_exp_f32_e32 v212, v212
	v_exp_f32_e32 v213, v213
	v_exp_f32_e32 v214, v214
	v_exp_f32_e32 v215, v215
	v_add_f32_e32 v212, 1.0, v212
	v_add_f32_e32 v213, 1.0, v213
	v_add_f32_e32 v214, 1.0, v214
	v_add_f32_e32 v215, 1.0, v215
	v_rcp_f32_e32 v212, v212
	v_rcp_f32_e32 v213, v213
	v_rcp_f32_e32 v214, v214
	v_rcp_f32_e32 v215, v215
	v_cvt_pk_bf16_f32 v154, v212, v213
	v_cvt_pk_bf16_f32 v155, v214, v215
	ds_write_b64 v151, v[154:155]
	s_waitcnt lgkmcnt(4)
; __device__ __forceinline__ float sigmoidf_(float x) { return __builtin_amdgcn_rcpf(1.0f + __expf(-x)); }
; template <int MODE> __device__ __forceinline__ void epi_store(const GemmDesc& g, int row, int col, f32x4 v) {
;     ...
;     case E_LW: {
;       const float4 bb = *(const float4*)(g.b0 + col);
;       _Float16 h0 = (_Float16)(0.60653065971263342f * sigmoidf_(v[0] + bb.x));
;       _Float16 h1 = (_Float16)(0.60653065971263342f * sigmoidf_(v[1] + bb.y));
;       _Float16 h2 = (_Float16)(0.60653065971263342f * sigmoidf_(v[2] + bb.z));
;       _Float16 h3 = (_Float16)(0.60653065971263342f * sigmoidf_(v[3] + bb.w));
;       _Float16* d = (_Float16*)g.o0 + (size_t)row * 1024 + col;
;     ...
;     case E_LA: {
;       const float4 bb = *(const float4*)(g.b0 + col);
;       uint2 o; o.x = pack2(sigmoidf_(v[0] + bb.x), sigmoidf_(v[1] + bb.y)); o.y = pack2(sigmoidf_(v[2] + bb.z), sigmoidf_(v[3] + bb.w));
;       *(uint2*)((u16*)g.o0 + (size_t)row * 1024 + col) = o;
;     } break;
	global_store_dwordx4 v146, v[236:239], s[66:67]
	global_store_dwordx4 v147, v[240:243], s[66:67]
	v_add_u32_e32 v146, 0x8000, v146
	v_add_u32_e32 v147, 0x8000, v147
	ds_read_b128 v[236:239], v156
	ds_read_b128 v[240:243], v156 offset:1024
	v_pk_add_f32 v[204:205], v[12:13], v[220:221]
	v_pk_add_f32 v[206:207], v[14:15], v[222:223]
	v_mul_f32_e32 v204, 0xbfb8aa3b, v204
	v_mul_f32_e32 v205, 0xbfb8aa3b, v205
	v_mul_f32_e32 v206, 0xbfb8aa3b, v206
	v_mul_f32_e32 v207, 0xbfb8aa3b, v207
	v_exp_f32_e32 v204, v204
	v_exp_f32_e32 v205, v205
	v_exp_f32_e32 v206, v206
	v_exp_f32_e32 v207, v207
	v_add_f32_e32 v204, 1.0, v204
	v_add_f32_e32 v205, 1.0, v205
	v_add_f32_e32 v206, 1.0, v206
	v_add_f32_e32 v207, 1.0, v207
	v_rcp_f32_e32 v204, v204
	v_rcp_f32_e32 v205, v205
	v_rcp_f32_e32 v206, v206
	v_rcp_f32_e32 v207, v207
	v_cvt_pk_bf16_f32 v152, v204, v205
	v_cvt_pk_bf16_f32 v153, v206, v207
	ds_write_b64 v148, v[152:153]
	v_pk_add_f32 v[212:213], v[8:9], v[224:225]
	v_pk_add_f32 v[214:215], v[10:11], v[226:227]
	v_mul_f32_e32 v212, 0xbfb8aa3b, v212
	v_mul_f32_e32 v213, 0xbfb8aa3b, v213
	v_mul_f32_e32 v214, 0xbfb8aa3b, v214
	v_mul_f32_e32 v215, 0xbfb8aa3b, v215
	v_exp_f32_e32 v212, v212
	v_exp_f32_e32 v213, v213
	v_exp_f32_e32 v214, v214
	v_exp_f32_e32 v215, v215
	v_add_f32_e32 v212, 1.0, v212
	v_add_f32_e32 v213, 1.0, v213
	v_add_f32_e32 v214, 1.0, v214
	v_add_f32_e32 v215, 1.0, v215
	v_rcp_f32_e32 v212, v212
	v_rcp_f32_e32 v213, v213
	v_rcp_f32_e32 v214, v214
	v_rcp_f32_e32 v215, v215
	v_cvt_pk_bf16_f32 v154, v212, v213
	v_cvt_pk_bf16_f32 v155, v214, v215
	ds_write_b64 v149, v[154:155]
	v_pk_add_f32 v[204:205], v[4:5], v[228:229]
	v_pk_add_f32 v[206:207], v[6:7], v[230:231]
	v_mul_f32_e32 v204, 0xbfb8aa3b, v204
	v_mul_f32_e32 v205, 0xbfb8aa3b, v205
	v_mul_f32_e32 v206, 0xbfb8aa3b, v206
	v_mul_f32_e32 v207, 0xbfb8aa3b, v207
	v_exp_f32_e32 v204, v204
	v_exp_f32_e32 v205, v205
	v_exp_f32_e32 v206, v206
	v_exp_f32_e32 v207, v207
	v_add_f32_e32 v204, 1.0, v204
	v_add_f32_e32 v205, 1.0, v205
	v_add_f32_e32 v206, 1.0, v206
	v_add_f32_e32 v207, 1.0, v207
	v_rcp_f32_e32 v204, v204
	v_rcp_f32_e32 v205, v205
	v_rcp_f32_e32 v206, v206
	v_rcp_f32_e32 v207, v207
	v_cvt_pk_bf16_f32 v152, v204, v205
	v_cvt_pk_bf16_f32 v153, v206, v207
	ds_write_b64 v150, v[152:153]
	v_pk_add_f32 v[212:213], v[0:1], v[232:233]
	v_pk_add_f32 v[214:215], v[2:3], v[234:235]
	v_mul_f32_e32 v212, 0xbfb8aa3b, v212
	v_mul_f32_e32 v213, 0xbfb8aa3b, v213
	v_mul_f32_e32 v214, 0xbfb8aa3b, v214
	v_mul_f32_e32 v215, 0xbfb8aa3b, v215
	v_exp_f32_e32 v212, v212
	v_exp_f32_e32 v213, v213
	v_exp_f32_e32 v214, v214
	v_exp_f32_e32 v215, v215
	v_add_f32_e32 v212, 1.0, v212
	v_add_f32_e32 v213, 1.0, v213
	v_add_f32_e32 v214, 1.0, v214
	v_add_f32_e32 v215, 1.0, v215
	v_rcp_f32_e32 v212, v212
	v_rcp_f32_e32 v213, v213
	v_rcp_f32_e32 v214, v214
	v_rcp_f32_e32 v215, v215
	v_cvt_pk_bf16_f32 v154, v212, v213
	v_cvt_pk_bf16_f32 v155, v214, v215
	ds_write_b64 v151, v[154:155]
	s_waitcnt lgkmcnt(4)
	global_store_dwordx4 v146, v[236:239], s[66:67]
	global_store_dwordx4 v147, v[240:243], s[66:67]
	v_add_u32_e32 v146, 0x8000, v146
	v_add_u32_e32 v147, 0x8000, v147
	ds_read_b128 v[236:239], v156
	ds_read_b128 v[240:243], v156 offset:1024
	s_waitcnt lgkmcnt(0)
	global_store_dwordx4 v146, v[236:239], s[66:67]
	global_store_dwordx4 v147, v[240:243], s[66:67]
	s_branch .LBB0_261
.LBB0_299:
	s_andn2_b64 vcc, exec, s[4:5]
	s_cbranch_vccnz .LBB0_301
	v_or_b32_e32 v204, s38, v175
	v_lshlrev_b32_e32 v204, 2, v204
	global_load_dwordx4 v[220:223], v204, s[12:13]
	global_load_dwordx4 v[224:227], v204, s[12:13] offset:64
	global_load_dwordx4 v[228:231], v204, s[12:13] offset:128
	global_load_dwordx4 v[232:235], v204, s[12:13] offset:192
	v_and_b32_e32 v204, 63, v135
	v_and_b32_e32 v205, 15, v204
	v_lshrrev_b32_e32 v206, 4, v204
	v_lshrrev_b32_e32 v207, 3, v204
	v_and_b32_e32 v208, 7, v204
	v_lshrrev_b32_e32 v209, 8, v135
	v_bfe_u32 v210, v135, 6, 2
	v_lshrrev_b32_e32 v211, 6, v135
	v_lshlrev_b32_e32 v211, 11, v211
	v_add_u32_e32 v211, 0x20000, v211
	v_lshrrev_b32_e32 v212, 1, v206
	v_and_b32_e32 v213, 7, v205
	v_xor_b32_e32 v212, v212, v213
	v_lshlrev_b32_e32 v212, 4, v212
	v_and_b32_e32 v213, 1, v206
	v_lshl_add_u32 v212, v213, 3, v212
	v_lshl_add_u32 v212, v205, 7, v212
	v_add_u32_e32 v148, v211, v212
	v_xor_b32_e32 v149, 32, v148
	v_xor_b32_e32 v150, 64, v148
	v_xor_b32_e32 v151, 0x60, v148
	v_xor_b32_e32 v212, v208, v207
	v_lshlrev_b32_e32 v212, 4, v212
	v_lshl_add_u32 v212, v207, 7, v212
	v_add_u32_e32 v156, v211, v212
	v_lshl_add_u32 v212, v209, 7, v207
	v_add_u32_e32 v212, s39, v212
	v_lshlrev_b32_e32 v213, 3, v208
	v_lshl_add_u32 v213, v210, 6, v213
	v_add_u32_e32 v213, s38, v213
	v_lshlrev_b32_e32 v212, 10, v212
	v_add_lshl_u32 v146, v212, v213, 1
	v_add_u32_e32 v147, 0x4000, v146
	s_waitcnt vmcnt(0)
; __device__ __forceinline__ float sigmoidf_(float x) { return __builtin_amdgcn_rcpf(1.0f + __expf(-x)); }
; template <int MODE> __device__ __forceinline__ void epi_store(const GemmDesc& g, int row, int col, f32x4 v) {
;     ...
;     case E_LW: {
;       const float4 bb = *(const float4*)(g.b0 + col);
;       _Float16 h0 = (_Float16)(0.60653065971263342f * sigmoidf_(v[0] + bb.x));
;       _Float16 h1 = (_Float16)(0.60653065971263342f * sigmoidf_(v[1] + bb.y));
;       _Float16 h2 = (_Float16)(0.60653065971263342f * sigmoidf_(v[2] + bb.z));
;       _Float16 h3 = (_Float16)(0.60653065971263342f * sigmoidf_(v[3] + bb.w));
;       _Float16* d = (_Float16*)g.o0 + (size_t)row * 1024 + col;
;       typedef _Float16 h4 __attribute__((ext_vector_type(4)));
;       h4 hv = {h0, h1, h2, h3};
;       *(h4*)d = hv;
;     } break;
	v_pk_add_f32 v[204:205], v[124:125], v[220:221]
	v_pk_add_f32 v[206:207], v[126:127], v[222:223]
	v_mul_f32_e32 v204, 0xbfb8aa3b, v204
	v_mul_f32_e32 v205, 0xbfb8aa3b, v205
	v_mul_f32_e32 v206, 0xbfb8aa3b, v206
	v_mul_f32_e32 v207, 0xbfb8aa3b, v207
	v_exp_f32_e32 v204, v204
	v_exp_f32_e32 v205, v205
	v_exp_f32_e32 v206, v206
	v_exp_f32_e32 v207, v207
	v_add_f32_e32 v204, 1.0, v204
	v_add_f32_e32 v205, 1.0, v205
	v_add_f32_e32 v206, 1.0, v206
	v_add_f32_e32 v207, 1.0, v207
	v_rcp_f32_e32 v204, v204
	v_rcp_f32_e32 v205, v205
	v_rcp_f32_e32 v206, v206
	v_rcp_f32_e32 v207, v207
	v_fma_mixlo_f16 v204, v204, s48, 0
	v_mul_f32_e32 v205, s48, v205
	v_mul_f32_e32 v206, s48, v206
	v_fma_mixlo_f16 v207, v207, s48, 0
	v_cvt_pk_f16_f32 v205, v205, v206
	v_pack_b32_f16 v152, v204, v205
	v_alignbit_b32 v153, v207, v205, 16
	ds_write_b64 v148, v[152:153]
	v_pk_add_f32 v[212:213], v[120:121], v[224:225]
	v_pk_add_f32 v[214:215], v[122:123], v[226:227]
	v_mul_f32_e32 v212, 0xbfb8aa3b, v212
	v_mul_f32_e32 v213, 0xbfb8aa3b, v213
	v_mul_f32_e32 v214, 0xbfb8aa3b, v214
	v_mul_f32_e32 v215, 0xbfb8aa3b, v215
	v_exp_f32_e32 v212, v212
	v_exp_f32_e32 v213, v213
	v_exp_f32_e32 v214, v214
	v_exp_f32_e32 v215, v215
	v_add_f32_e32 v212, 1.0, v212
	v_add_f32_e32 v213, 1.0, v213
	v_add_f32_e32 v214, 1.0, v214
	v_add_f32_e32 v215, 1.0, v215
	v_rcp_f32_e32 v212, v212
	v_rcp_f32_e32 v213, v213
	v_rcp_f32_e32 v214, v214
	v_rcp_f32_e32 v215, v215
	v_fma_mixlo_f16 v212, v212, s48, 0
	v_mul_f32_e32 v213, s48, v213
	v_mul_f32_e32 v214, s48, v214
	v_fma_mixlo_f16 v215, v215, s48, 0
	v_cvt_pk_f16_f32 v213, v213, v214
	v_pack_b32_f16 v154, v212, v213
	v_alignbit_b32 v155, v215, v213, 16
	ds_write_b64 v149, v[154:155]
	v_pk_add_f32 v[204:205], v[116:117], v[228:229]
	v_pk_add_f32 v[206:207], v[118:119], v[230:231]
	v_mul_f32_e32 v204, 0xbfb8aa3b, v204
	v_mul_f32_e32 v205, 0xbfb8aa3b, v205
	v_mul_f32_e32 v206, 0xbfb8aa3b, v206
	v_mul_f32_e32 v207, 0xbfb8aa3b, v207
	v_exp_f32_e32 v204, v204
	v_exp_f32_e32 v205, v205
	v_exp_f32_e32 v206, v206
	v_exp_f32_e32 v207, v207
	v_add_f32_e32 v204, 1.0, v204
	v_add_f32_e32 v205, 1.0, v205
	v_add_f32_e32 v206, 1.0, v206
	v_add_f32_e32 v207, 1.0, v207
	v_rcp_f32_e32 v204, v204
	v_rcp_f32_e32 v205, v205
	v_rcp_f32_e32 v206, v206
	v_rcp_f32_e32 v207, v207
	v_fma_mixlo_f16 v204, v204, s48, 0
	v_mul_f32_e32 v205, s48, v205
	v_mul_f32_e32 v206, s48, v206
	v_fma_mixlo_f16 v207, v207, s48, 0
	v_cvt_pk_f16_f32 v205, v205, v206
	v_pack_b32_f16 v152, v204, v205
	v_alignbit_b32 v153, v207, v205, 16
	ds_write_b64 v150, v[152:153]
	v_pk_add_f32 v[212:213], v[112:113], v[232:233]
	v_pk_add_f32 v[214:215], v[114:115], v[234:235]
	v_mul_f32_e32 v212, 0xbfb8aa3b, v212
	v_mul_f32_e32 v213, 0xbfb8aa3b, v213
	v_mul_f32_e32 v214, 0xbfb8aa3b, v214
	v_mul_f32_e32 v215, 0xbfb8aa3b, v215
	v_exp_f32_e32 v212, v212
	v_exp_f32_e32 v213, v213
	v_exp_f32_e32 v214, v214
	v_exp_f32_e32 v215, v215
	v_add_f32_e32 v212, 1.0, v212
	v_add_f32_e32 v213, 1.0, v213
	v_add_f32_e32 v214, 1.0, v214
	v_add_f32_e32 v215, 1.0, v215
	v_rcp_f32_e32 v212, v212
	v_rcp_f32_e32 v213, v213
	v_rcp_f32_e32 v214, v214
	v_rcp_f32_e32 v215, v215
	v_fma_mixlo_f16 v212, v212, s48, 0
	v_mul_f32_e32 v213, s48, v213
	v_mul_f32_e32 v214, s48, v214
	v_fma_mixlo_f16 v215, v215, s48, 0
	v_cvt_pk_f16_f32 v213, v213, v214
	v_pack_b32_f16 v154, v212, v213
	v_alignbit_b32 v155, v215, v213, 16
	ds_write_b64 v151, v[154:155]
	ds_read_b128 v[236:239], v156
	ds_read_b128 v[240:243], v156 offset:1024
	v_pk_add_f32 v[204:205], v[108:109], v[220:221]
	v_pk_add_f32 v[206:207], v[110:111], v[222:223]
	v_mul_f32_e32 v204, 0xbfb8aa3b, v204
	v_mul_f32_e32 v205, 0xbfb8aa3b, v205
	v_mul_f32_e32 v206, 0xbfb8aa3b, v206
	v_mul_f32_e32 v207, 0xbfb8aa3b, v207
	v_exp_f32_e32 v204, v204
	v_exp_f32_e32 v205, v205
	v_exp_f32_e32 v206, v206
	v_exp_f32_e32 v207, v207
	v_add_f32_e32 v204, 1.0, v204
	v_add_f32_e32 v205, 1.0, v205
	v_add_f32_e32 v206, 1.0, v206
	v_add_f32_e32 v207, 1.0, v207
	v_rcp_f32_e32 v204, v204
	v_rcp_f32_e32 v205, v205
	v_rcp_f32_e32 v206, v206
	v_rcp_f32_e32 v207, v207
	v_fma_mixlo_f16 v204, v204, s48, 0
	v_mul_f32_e32 v205, s48, v205
	v_mul_f32_e32 v206, s48, v206
	v_fma_mixlo_f16 v207, v207, s48, 0
	v_cvt_pk_f16_f32 v205, v205, v206
	v_pack_b32_f16 v152, v204, v205
	v_alignbit_b32 v153, v207, v205, 16
	ds_write_b64 v148, v[152:153]
	v_pk_add_f32 v[212:213], v[104:105], v[224:225]
	v_pk_add_f32 v[214:215], v[106:107], v[226:227]
	v_mul_f32_e32 v212, 0xbfb8aa3b, v212
	v_mul_f32_e32 v213, 0xbfb8aa3b, v213
	v_mul_f32_e32 v214, 0xbfb8aa3b, v214
	v_mul_f32_e32 v215, 0xbfb8aa3b, v215
	v_exp_f32_e32 v212, v212
	v_exp_f32_e32 v213, v213
	v_exp_f32_e32 v214, v214
	v_exp_f32_e32 v215, v215
	v_add_f32_e32 v212, 1.0, v212
	v_add_f32_e32 v213, 1.0, v213
	v_add_f32_e32 v214, 1.0, v214
	v_add_f32_e32 v215, 1.0, v215
	v_rcp_f32_e32 v212, v212
	v_rcp_f32_e32 v213, v213
	v_rcp_f32_e32 v214, v214
	v_rcp_f32_e32 v215, v215
	v_fma_mixlo_f16 v212, v212, s48, 0
	v_mul_f32_e32 v213, s48, v213
	v_mul_f32_e32 v214, s48, v214
	v_fma_mixlo_f16 v215, v215, s48, 0
	v_cvt_pk_f16_f32 v213, v213, v214
	v_pack_b32_f16 v154, v212, v213
	v_alignbit_b32 v155, v215, v213, 16
	ds_write_b64 v149, v[154:155]
	v_pk_add_f32 v[204:205], v[100:101], v[228:229]
	v_pk_add_f32 v[206:207], v[102:103], v[230:231]
	v_mul_f32_e32 v204, 0xbfb8aa3b, v204
	v_mul_f32_e32 v205, 0xbfb8aa3b, v205
	v_mul_f32_e32 v206, 0xbfb8aa3b, v206
	v_mul_f32_e32 v207, 0xbfb8aa3b, v207
	v_exp_f32_e32 v204, v204
	v_exp_f32_e32 v205, v205
	v_exp_f32_e32 v206, v206
	v_exp_f32_e32 v207, v207
	v_add_f32_e32 v204, 1.0, v204
	v_add_f32_e32 v205, 1.0, v205
	v_add_f32_e32 v206, 1.0, v206
	v_add_f32_e32 v207, 1.0, v207
	v_rcp_f32_e32 v204, v204
	v_rcp_f32_e32 v205, v205
	v_rcp_f32_e32 v206, v206
	v_rcp_f32_e32 v207, v207
	v_fma_mixlo_f16 v204, v204, s48, 0
	v_mul_f32_e32 v205, s48, v205
	v_mul_f32_e32 v206, s48, v206
	v_fma_mixlo_f16 v207, v207, s48, 0
	v_cvt_pk_f16_f32 v205, v205, v206
	v_pack_b32_f16 v152, v204, v205
	v_alignbit_b32 v153, v207, v205, 16
	ds_write_b64 v150, v[152:153]
	v_pk_add_f32 v[212:213], v[96:97], v[232:233]
	v_pk_add_f32 v[214:215], v[98:99], v[234:235]
	v_mul_f32_e32 v212, 0xbfb8aa3b, v212
	v_mul_f32_e32 v213, 0xbfb8aa3b, v213
	v_mul_f32_e32 v214, 0xbfb8aa3b, v214
	v_mul_f32_e32 v215, 0xbfb8aa3b, v215
	v_exp_f32_e32 v212, v212
	v_exp_f32_e32 v213, v213
	v_exp_f32_e32 v214, v214
	v_exp_f32_e32 v215, v215
	v_add_f32_e32 v212, 1.0, v212
	v_add_f32_e32 v213, 1.0, v213
	v_add_f32_e32 v214, 1.0, v214
	v_add_f32_e32 v215, 1.0, v215
	v_rcp_f32_e32 v212, v212
	v_rcp_f32_e32 v213, v213
	v_rcp_f32_e32 v214, v214
	v_rcp_f32_e32 v215, v215
	v_fma_mixlo_f16 v212, v212, s48, 0
	v_mul_f32_e32 v213, s48, v213
	v_mul_f32_e32 v214, s48, v214
	v_fma_mixlo_f16 v215, v215, s48, 0
	v_cvt_pk_f16_f32 v213, v213, v214
	v_pack_b32_f16 v154, v212, v213
	v_alignbit_b32 v155, v215, v213, 16
	ds_write_b64 v151, v[154:155]
	s_waitcnt lgkmcnt(4)
; __device__ __forceinline__ float sigmoidf_(float x) { return __builtin_amdgcn_rcpf(1.0f + __expf(-x)); }
; template <int MODE> __device__ __forceinline__ void epi_store(const GemmDesc& g, int row, int col, f32x4 v) {
;     ...
;     case E_LW: {
;       const float4 bb = *(const float4*)(g.b0 + col);
;       _Float16 h0 = (_Float16)(0.60653065971263342f * sigmoidf_(v[0] + bb.x));
;       _Float16 h1 = (_Float16)(0.60653065971263342f * sigmoidf_(v[1] + bb.y));
;       _Float16 h2 = (_Float16)(0.60653065971263342f * sigmoidf_(v[2] + bb.z));
;       _Float16 h3 = (_Float16)(0.60653065971263342f * sigmoidf_(v[3] + bb.w));
;       _Float16* d = (_Float16*)g.o0 + (size_t)row * 1024 + col;
;       typedef _Float16 h4 __attribute__((ext_vector_type(4)));
;       h4 hv = {h0, h1, h2, h3};
;       *(h4*)d = hv;
;     } break;
	global_store_dwordx4 v146, v[236:239], s[66:67]
	global_store_dwordx4 v147, v[240:243], s[66:67]
	v_add_u32_e32 v146, 0x8000, v146
	v_add_u32_e32 v147, 0x8000, v147
	ds_read_b128 v[236:239], v156
	ds_read_b128 v[240:243], v156 offset:1024
	v_pk_add_f32 v[204:205], v[92:93], v[220:221]
	v_pk_add_f32 v[206:207], v[94:95], v[222:223]
	v_mul_f32_e32 v204, 0xbfb8aa3b, v204
	v_mul_f32_e32 v205, 0xbfb8aa3b, v205
	v_mul_f32_e32 v206, 0xbfb8aa3b, v206
	v_mul_f32_e32 v207, 0xbfb8aa3b, v207
	v_exp_f32_e32 v204, v204
	v_exp_f32_e32 v205, v205
	v_exp_f32_e32 v206, v206
	v_exp_f32_e32 v207, v207
	v_add_f32_e32 v204, 1.0, v204
	v_add_f32_e32 v205, 1.0, v205
	v_add_f32_e32 v206, 1.0, v206
	v_add_f32_e32 v207, 1.0, v207
	v_rcp_f32_e32 v204, v204
	v_rcp_f32_e32 v205, v205
	v_rcp_f32_e32 v206, v206
	v_rcp_f32_e32 v207, v207
	v_fma_mixlo_f16 v204, v204, s48, 0
	v_mul_f32_e32 v205, s48, v205
	v_mul_f32_e32 v206, s48, v206
	v_fma_mixlo_f16 v207, v207, s48, 0
	v_cvt_pk_f16_f32 v205, v205, v206
	v_pack_b32_f16 v152, v204, v205
	v_alignbit_b32 v153, v207, v205, 16
	ds_write_b64 v148, v[152:153]
	v_pk_add_f32 v[212:213], v[88:89], v[224:225]
	v_pk_add_f32 v[214:215], v[90:91], v[226:227]
	v_mul_f32_e32 v212, 0xbfb8aa3b, v212
	v_mul_f32_e32 v213, 0xbfb8aa3b, v213
	v_mul_f32_e32 v214, 0xbfb8aa3b, v214
	v_mul_f32_e32 v215, 0xbfb8aa3b, v215
	v_exp_f32_e32 v212, v212
	v_exp_f32_e32 v213, v213
	v_exp_f32_e32 v214, v214
	v_exp_f32_e32 v215, v215
	v_add_f32_e32 v212, 1.0, v212
	v_add_f32_e32 v213, 1.0, v213
	v_add_f32_e32 v214, 1.0, v214
	v_add_f32_e32 v215, 1.0, v215
	v_rcp_f32_e32 v212, v212
	v_rcp_f32_e32 v213, v213
	v_rcp_f32_e32 v214, v214
	v_rcp_f32_e32 v215, v215
	v_fma_mixlo_f16 v212, v212, s48, 0
	v_mul_f32_e32 v213, s48, v213
	v_mul_f32_e32 v214, s48, v214
	v_fma_mixlo_f16 v215, v215, s48, 0
	v_cvt_pk_f16_f32 v213, v213, v214
	v_pack_b32_f16 v154, v212, v213
	v_alignbit_b32 v155, v215, v213, 16
	ds_write_b64 v149, v[154:155]
	v_pk_add_f32 v[204:205], v[84:85], v[228:229]
	v_pk_add_f32 v[206:207], v[86:87], v[230:231]
	v_mul_f32_e32 v204, 0xbfb8aa3b, v204
	v_mul_f32_e32 v205, 0xbfb8aa3b, v205
	v_mul_f32_e32 v206, 0xbfb8aa3b, v206
	v_mul_f32_e32 v207, 0xbfb8aa3b, v207
	v_exp_f32_e32 v204, v204
	v_exp_f32_e32 v205, v205
	v_exp_f32_e32 v206, v206
	v_exp_f32_e32 v207, v207
	v_add_f32_e32 v204, 1.0, v204
	v_add_f32_e32 v205, 1.0, v205
	v_add_f32_e32 v206, 1.0, v206
	v_add_f32_e32 v207, 1.0, v207
	v_rcp_f32_e32 v204, v204
	v_rcp_f32_e32 v205, v205
	v_rcp_f32_e32 v206, v206
	v_rcp_f32_e32 v207, v207
	v_fma_mixlo_f16 v204, v204, s48, 0
	v_mul_f32_e32 v205, s48, v205
	v_mul_f32_e32 v206, s48, v206
	v_fma_mixlo_f16 v207, v207, s48, 0
	v_cvt_pk_f16_f32 v205, v205, v206
	v_pack_b32_f16 v152, v204, v205
	v_alignbit_b32 v153, v207, v205, 16
	ds_write_b64 v150, v[152:153]
	v_pk_add_f32 v[212:213], v[80:81], v[232:233]
	v_pk_add_f32 v[214:215], v[82:83], v[234:235]
	v_mul_f32_e32 v212, 0xbfb8aa3b, v212
	v_mul_f32_e32 v213, 0xbfb8aa3b, v213
	v_mul_f32_e32 v214, 0xbfb8aa3b, v214
	v_mul_f32_e32 v215, 0xbfb8aa3b, v215
	v_exp_f32_e32 v212, v212
	v_exp_f32_e32 v213, v213
	v_exp_f32_e32 v214, v214
	v_exp_f32_e32 v215, v215
	v_add_f32_e32 v212, 1.0, v212
	v_add_f32_e32 v213, 1.0, v213
	v_add_f32_e32 v214, 1.0, v214
	v_add_f32_e32 v215, 1.0, v215
	v_rcp_f32_e32 v212, v212
	v_rcp_f32_e32 v213, v213
	v_rcp_f32_e32 v214, v214
	v_rcp_f32_e32 v215, v215
	v_fma_mixlo_f16 v212, v212, s48, 0
	v_mul_f32_e32 v213, s48, v213
	v_mul_f32_e32 v214, s48, v214
	v_fma_mixlo_f16 v215, v215, s48, 0
	v_cvt_pk_f16_f32 v213, v213, v214
	v_pack_b32_f16 v154, v212, v213
	v_alignbit_b32 v155, v215, v213, 16
	ds_write_b64 v151, v[154:155]
	s_waitcnt lgkmcnt(4)
	global_store_dwordx4 v146, v[236:239], s[66:67]
	global_store_dwordx4 v147, v[240:243], s[66:67]
	v_add_u32_e32 v146, 0x8000, v146
	v_add_u32_e32 v147, 0x8000, v147
	ds_read_b128 v[236:239], v156
	ds_read_b128 v[240:243], v156 offset:1024
	v_pk_add_f32 v[204:205], v[76:77], v[220:221]
	v_pk_add_f32 v[206:207], v[78:79], v[222:223]
	v_mul_f32_e32 v204, 0xbfb8aa3b, v204
	v_mul_f32_e32 v205, 0xbfb8aa3b, v205
	v_mul_f32_e32 v206, 0xbfb8aa3b, v206
	v_mul_f32_e32 v207, 0xbfb8aa3b, v207
	v_exp_f32_e32 v204, v204
	v_exp_f32_e32 v205, v205
	v_exp_f32_e32 v206, v206
	v_exp_f32_e32 v207, v207
	v_add_f32_e32 v204, 1.0, v204
	v_add_f32_e32 v205, 1.0, v205
	v_add_f32_e32 v206, 1.0, v206
	v_add_f32_e32 v207, 1.0, v207
	v_rcp_f32_e32 v204, v204
	v_rcp_f32_e32 v205, v205
	v_rcp_f32_e32 v206, v206
	v_rcp_f32_e32 v207, v207
	v_fma_mixlo_f16 v204, v204, s48, 0
	v_mul_f32_e32 v205, s48, v205
	v_mul_f32_e32 v206, s48, v206
	v_fma_mixlo_f16 v207, v207, s48, 0
	v_cvt_pk_f16_f32 v205, v205, v206
	v_pack_b32_f16 v152, v204, v205
	v_alignbit_b32 v153, v207, v205, 16
	ds_write_b64 v148, v[152:153]
	v_pk_add_f32 v[212:213], v[72:73], v[224:225]
	v_pk_add_f32 v[214:215], v[74:75], v[226:227]
	v_mul_f32_e32 v212, 0xbfb8aa3b, v212
	v_mul_f32_e32 v213, 0xbfb8aa3b, v213
	v_mul_f32_e32 v214, 0xbfb8aa3b, v214
	v_mul_f32_e32 v215, 0xbfb8aa3b, v215
	v_exp_f32_e32 v212, v212
	v_exp_f32_e32 v213, v213
	v_exp_f32_e32 v214, v214
	v_exp_f32_e32 v215, v215
	v_add_f32_e32 v212, 1.0, v212
	v_add_f32_e32 v213, 1.0, v213
	v_add_f32_e32 v214, 1.0, v214
	v_add_f32_e32 v215, 1.0, v215
	v_rcp_f32_e32 v212, v212
	v_rcp_f32_e32 v213, v213
	v_rcp_f32_e32 v214, v214
	v_rcp_f32_e32 v215, v215
	v_fma_mixlo_f16 v212, v212, s48, 0
	v_mul_f32_e32 v213, s48, v213
	v_mul_f32_e32 v214, s48, v214
	v_fma_mixlo_f16 v215, v215, s48, 0
	v_cvt_pk_f16_f32 v213, v213, v214
	v_pack_b32_f16 v154, v212, v213
	v_alignbit_b32 v155, v215, v213, 16
	ds_write_b64 v149, v[154:155]
	v_pk_add_f32 v[204:205], v[68:69], v[228:229]
; __device__ __forceinline__ float sigmoidf_(float x) { return __builtin_amdgcn_rcpf(1.0f + __expf(-x)); }
; template <int MODE> __device__ __forceinline__ void epi_store(const GemmDesc& g, int row, int col, f32x4 v) {
;     ...
;     case E_LW: {
;       const float4 bb = *(const float4*)(g.b0 + col);
;       _Float16 h0 = (_Float16)(0.60653065971263342f * sigmoidf_(v[0] + bb.x));
;       _Float16 h1 = (_Float16)(0.60653065971263342f * sigmoidf_(v[1] + bb.y));
;       _Float16 h2 = (_Float16)(0.60653065971263342f * sigmoidf_(v[2] + bb.z));
;       _Float16 h3 = (_Float16)(0.60653065971263342f * sigmoidf_(v[3] + bb.w));
;       _Float16* d = (_Float16*)g.o0 + (size_t)row * 1024 + col;
;       typedef _Float16 h4 __attribute__((ext_vector_type(4)));
;       h4 hv = {h0, h1, h2, h3};
;       *(h4*)d = hv;
;     } break;
	v_pk_add_f32 v[206:207], v[70:71], v[230:231]
	v_mul_f32_e32 v204, 0xbfb8aa3b, v204
	v_mul_f32_e32 v205, 0xbfb8aa3b, v205
	v_mul_f32_e32 v206, 0xbfb8aa3b, v206
	v_mul_f32_e32 v207, 0xbfb8aa3b, v207
	v_exp_f32_e32 v204, v204
	v_exp_f32_e32 v205, v205
	v_exp_f32_e32 v206, v206
	v_exp_f32_e32 v207, v207
	v_add_f32_e32 v204, 1.0, v204
	v_add_f32_e32 v205, 1.0, v205
	v_add_f32_e32 v206, 1.0, v206
	v_add_f32_e32 v207, 1.0, v207
	v_rcp_f32_e32 v204, v204
	v_rcp_f32_e32 v205, v205
	v_rcp_f32_e32 v206, v206
	v_rcp_f32_e32 v207, v207
	v_fma_mixlo_f16 v204, v204, s48, 0
	v_mul_f32_e32 v205, s48, v205
	v_mul_f32_e32 v206, s48, v206
	v_fma_mixlo_f16 v207, v207, s48, 0
	v_cvt_pk_f16_f32 v205, v205, v206
	v_pack_b32_f16 v152, v204, v205
	v_alignbit_b32 v153, v207, v205, 16
	ds_write_b64 v150, v[152:153]
	v_pk_add_f32 v[212:213], v[64:65], v[232:233]
	v_pk_add_f32 v[214:215], v[66:67], v[234:235]
	v_mul_f32_e32 v212, 0xbfb8aa3b, v212
	v_mul_f32_e32 v213, 0xbfb8aa3b, v213
	v_mul_f32_e32 v214, 0xbfb8aa3b, v214
	v_mul_f32_e32 v215, 0xbfb8aa3b, v215
	v_exp_f32_e32 v212, v212
	v_exp_f32_e32 v213, v213
	v_exp_f32_e32 v214, v214
	v_exp_f32_e32 v215, v215
	v_add_f32_e32 v212, 1.0, v212
	v_add_f32_e32 v213, 1.0, v213
	v_add_f32_e32 v214, 1.0, v214
	v_add_f32_e32 v215, 1.0, v215
	v_rcp_f32_e32 v212, v212
	v_rcp_f32_e32 v213, v213
	v_rcp_f32_e32 v214, v214
	v_rcp_f32_e32 v215, v215
	v_fma_mixlo_f16 v212, v212, s48, 0
	v_mul_f32_e32 v213, s48, v213
	v_mul_f32_e32 v214, s48, v214
	v_fma_mixlo_f16 v215, v215, s48, 0
	v_cvt_pk_f16_f32 v213, v213, v214
	v_pack_b32_f16 v154, v212, v213
	v_alignbit_b32 v155, v215, v213, 16
	ds_write_b64 v151, v[154:155]
	s_waitcnt lgkmcnt(4)
	global_store_dwordx4 v146, v[236:239], s[66:67]
	global_store_dwordx4 v147, v[240:243], s[66:67]
	v_add_u32_e32 v146, 0x8000, v146
	v_add_u32_e32 v147, 0x8000, v147
	ds_read_b128 v[236:239], v156
	ds_read_b128 v[240:243], v156 offset:1024
	v_pk_add_f32 v[204:205], v[60:61], v[220:221]
	v_pk_add_f32 v[206:207], v[62:63], v[222:223]
	v_mul_f32_e32 v204, 0xbfb8aa3b, v204
	v_mul_f32_e32 v205, 0xbfb8aa3b, v205
	v_mul_f32_e32 v206, 0xbfb8aa3b, v206
	v_mul_f32_e32 v207, 0xbfb8aa3b, v207
	v_exp_f32_e32 v204, v204
	v_exp_f32_e32 v205, v205
	v_exp_f32_e32 v206, v206
	v_exp_f32_e32 v207, v207
	v_add_f32_e32 v204, 1.0, v204
	v_add_f32_e32 v205, 1.0, v205
	v_add_f32_e32 v206, 1.0, v206
	v_add_f32_e32 v207, 1.0, v207
	v_rcp_f32_e32 v204, v204
	v_rcp_f32_e32 v205, v205
	v_rcp_f32_e32 v206, v206
	v_rcp_f32_e32 v207, v207
	v_fma_mixlo_f16 v204, v204, s48, 0
	v_mul_f32_e32 v205, s48, v205
	v_mul_f32_e32 v206, s48, v206
	v_fma_mixlo_f16 v207, v207, s48, 0
	v_cvt_pk_f16_f32 v205, v205, v206
	v_pack_b32_f16 v152, v204, v205
	v_alignbit_b32 v153, v207, v205, 16
	ds_write_b64 v148, v[152:153]
	v_pk_add_f32 v[212:213], v[56:57], v[224:225]
	v_pk_add_f32 v[214:215], v[58:59], v[226:227]
	v_mul_f32_e32 v212, 0xbfb8aa3b, v212
	v_mul_f32_e32 v213, 0xbfb8aa3b, v213
	v_mul_f32_e32 v214, 0xbfb8aa3b, v214
	v_mul_f32_e32 v215, 0xbfb8aa3b, v215
	v_exp_f32_e32 v212, v212
	v_exp_f32_e32 v213, v213
	v_exp_f32_e32 v214, v214
	v_exp_f32_e32 v215, v215
	v_add_f32_e32 v212, 1.0, v212
	v_add_f32_e32 v213, 1.0, v213
	v_add_f32_e32 v214, 1.0, v214
	v_add_f32_e32 v215, 1.0, v215
	v_rcp_f32_e32 v212, v212
	v_rcp_f32_e32 v213, v213
	v_rcp_f32_e32 v214, v214
	v_rcp_f32_e32 v215, v215
	v_fma_mixlo_f16 v212, v212, s48, 0
	v_mul_f32_e32 v213, s48, v213
	v_mul_f32_e32 v214, s48, v214
	v_fma_mixlo_f16 v215, v215, s48, 0
	v_cvt_pk_f16_f32 v213, v213, v214
	v_pack_b32_f16 v154, v212, v213
	v_alignbit_b32 v155, v215, v213, 16
	ds_write_b64 v149, v[154:155]
	v_pk_add_f32 v[204:205], v[52:53], v[228:229]
	v_pk_add_f32 v[206:207], v[54:55], v[230:231]
	v_mul_f32_e32 v204, 0xbfb8aa3b, v204
	v_mul_f32_e32 v205, 0xbfb8aa3b, v205
	v_mul_f32_e32 v206, 0xbfb8aa3b, v206
	v_mul_f32_e32 v207, 0xbfb8aa3b, v207
	v_exp_f32_e32 v204, v204
	v_exp_f32_e32 v205, v205
	v_exp_f32_e32 v206, v206
	v_exp_f32_e32 v207, v207
	v_add_f32_e32 v204, 1.0, v204
	v_add_f32_e32 v205, 1.0, v205
	v_add_f32_e32 v206, 1.0, v206
	v_add_f32_e32 v207, 1.0, v207
	v_rcp_f32_e32 v204, v204
	v_rcp_f32_e32 v205, v205
	v_rcp_f32_e32 v206, v206
	v_rcp_f32_e32 v207, v207
	v_fma_mixlo_f16 v204, v204, s48, 0
	v_mul_f32_e32 v205, s48, v205
	v_mul_f32_e32 v206, s48, v206
	v_fma_mixlo_f16 v207, v207, s48, 0
	v_cvt_pk_f16_f32 v205, v205, v206
	v_pack_b32_f16 v152, v204, v205
	v_alignbit_b32 v153, v207, v205, 16
	ds_write_b64 v150, v[152:153]
	v_pk_add_f32 v[212:213], v[48:49], v[232:233]
	v_pk_add_f32 v[214:215], v[50:51], v[234:235]
	v_mul_f32_e32 v212, 0xbfb8aa3b, v212
	v_mul_f32_e32 v213, 0xbfb8aa3b, v213
	v_mul_f32_e32 v214, 0xbfb8aa3b, v214
	v_mul_f32_e32 v215, 0xbfb8aa3b, v215
	v_exp_f32_e32 v212, v212
	v_exp_f32_e32 v213, v213
	v_exp_f32_e32 v214, v214
	v_exp_f32_e32 v215, v215
	v_add_f32_e32 v212, 1.0, v212
	v_add_f32_e32 v213, 1.0, v213
	v_add_f32_e32 v214, 1.0, v214
	v_add_f32_e32 v215, 1.0, v215
	v_rcp_f32_e32 v212, v212
	v_rcp_f32_e32 v213, v213
	v_rcp_f32_e32 v214, v214
	v_rcp_f32_e32 v215, v215
	v_fma_mixlo_f16 v212, v212, s48, 0
	v_mul_f32_e32 v213, s48, v213
	v_mul_f32_e32 v214, s48, v214
	v_fma_mixlo_f16 v215, v215, s48, 0
	v_cvt_pk_f16_f32 v213, v213, v214
	v_pack_b32_f16 v154, v212, v213
	v_alignbit_b32 v155, v215, v213, 16
	ds_write_b64 v151, v[154:155]
	s_waitcnt lgkmcnt(4)
; __device__ __forceinline__ float sigmoidf_(float x) { return __builtin_amdgcn_rcpf(1.0f + __expf(-x)); }
; template <int MODE> __device__ __forceinline__ void epi_store(const GemmDesc& g, int row, int col, f32x4 v) {
;     ...
;     case E_LW: {
;       const float4 bb = *(const float4*)(g.b0 + col);
;       _Float16 h0 = (_Float16)(0.60653065971263342f * sigmoidf_(v[0] + bb.x));
;       _Float16 h1 = (_Float16)(0.60653065971263342f * sigmoidf_(v[1] + bb.y));
;       _Float16 h2 = (_Float16)(0.60653065971263342f * sigmoidf_(v[2] + bb.z));
;       _Float16 h3 = (_Float16)(0.60653065971263342f * sigmoidf_(v[3] + bb.w));
;       _Float16* d = (_Float16*)g.o0 + (size_t)row * 1024 + col;
;       typedef _Float16 h4 __attribute__((ext_vector_type(4)));
;       h4 hv = {h0, h1, h2, h3};
;       *(h4*)d = hv;
;     } break;
	global_store_dwordx4 v146, v[236:239], s[66:67]
	global_store_dwordx4 v147, v[240:243], s[66:67]
	v_add_u32_e32 v146, 0x8000, v146
	v_add_u32_e32 v147, 0x8000, v147
	ds_read_b128 v[236:239], v156
	ds_read_b128 v[240:243], v156 offset:1024
	v_pk_add_f32 v[204:205], v[44:45], v[220:221]
	v_pk_add_f32 v[206:207], v[46:47], v[222:223]
	v_mul_f32_e32 v204, 0xbfb8aa3b, v204
	v_mul_f32_e32 v205, 0xbfb8aa3b, v205
	v_mul_f32_e32 v206, 0xbfb8aa3b, v206
	v_mul_f32_e32 v207, 0xbfb8aa3b, v207
	v_exp_f32_e32 v204, v204
	v_exp_f32_e32 v205, v205
	v_exp_f32_e32 v206, v206
	v_exp_f32_e32 v207, v207
	v_add_f32_e32 v204, 1.0, v204
	v_add_f32_e32 v205, 1.0, v205
	v_add_f32_e32 v206, 1.0, v206
	v_add_f32_e32 v207, 1.0, v207
	v_rcp_f32_e32 v204, v204
	v_rcp_f32_e32 v205, v205
	v_rcp_f32_e32 v206, v206
	v_rcp_f32_e32 v207, v207
	v_fma_mixlo_f16 v204, v204, s48, 0
	v_mul_f32_e32 v205, s48, v205
	v_mul_f32_e32 v206, s48, v206
	v_fma_mixlo_f16 v207, v207, s48, 0
	v_cvt_pk_f16_f32 v205, v205, v206
	v_pack_b32_f16 v152, v204, v205
	v_alignbit_b32 v153, v207, v205, 16
	ds_write_b64 v148, v[152:153]
	v_pk_add_f32 v[212:213], v[40:41], v[224:225]
	v_pk_add_f32 v[214:215], v[42:43], v[226:227]
	v_mul_f32_e32 v212, 0xbfb8aa3b, v212
	v_mul_f32_e32 v213, 0xbfb8aa3b, v213
	v_mul_f32_e32 v214, 0xbfb8aa3b, v214
	v_mul_f32_e32 v215, 0xbfb8aa3b, v215
	v_exp_f32_e32 v212, v212
	v_exp_f32_e32 v213, v213
	v_exp_f32_e32 v214, v214
	v_exp_f32_e32 v215, v215
	v_add_f32_e32 v212, 1.0, v212
	v_add_f32_e32 v213, 1.0, v213
	v_add_f32_e32 v214, 1.0, v214
	v_add_f32_e32 v215, 1.0, v215
	v_rcp_f32_e32 v212, v212
	v_rcp_f32_e32 v213, v213
	v_rcp_f32_e32 v214, v214
	v_rcp_f32_e32 v215, v215
	v_fma_mixlo_f16 v212, v212, s48, 0
	v_mul_f32_e32 v213, s48, v213
	v_mul_f32_e32 v214, s48, v214
	v_fma_mixlo_f16 v215, v215, s48, 0
	v_cvt_pk_f16_f32 v213, v213, v214
	v_pack_b32_f16 v154, v212, v213
	v_alignbit_b32 v155, v215, v213, 16
	ds_write_b64 v149, v[154:155]
	v_pk_add_f32 v[204:205], v[36:37], v[228:229]
	v_pk_add_f32 v[206:207], v[38:39], v[230:231]
	v_mul_f32_e32 v204, 0xbfb8aa3b, v204
	v_mul_f32_e32 v205, 0xbfb8aa3b, v205
	v_mul_f32_e32 v206, 0xbfb8aa3b, v206
	v_mul_f32_e32 v207, 0xbfb8aa3b, v207
	v_exp_f32_e32 v204, v204
	v_exp_f32_e32 v205, v205
	v_exp_f32_e32 v206, v206
	v_exp_f32_e32 v207, v207
	v_add_f32_e32 v204, 1.0, v204
	v_add_f32_e32 v205, 1.0, v205
	v_add_f32_e32 v206, 1.0, v206
	v_add_f32_e32 v207, 1.0, v207
	v_rcp_f32_e32 v204, v204
	v_rcp_f32_e32 v205, v205
	v_rcp_f32_e32 v206, v206
	v_rcp_f32_e32 v207, v207
	v_fma_mixlo_f16 v204, v204, s48, 0
	v_mul_f32_e32 v205, s48, v205
	v_mul_f32_e32 v206, s48, v206
	v_fma_mixlo_f16 v207, v207, s48, 0
	v_cvt_pk_f16_f32 v205, v205, v206
	v_pack_b32_f16 v152, v204, v205
	v_alignbit_b32 v153, v207, v205, 16
	ds_write_b64 v150, v[152:153]
	v_pk_add_f32 v[212:213], v[32:33], v[232:233]
	v_pk_add_f32 v[214:215], v[34:35], v[234:235]
	v_mul_f32_e32 v212, 0xbfb8aa3b, v212
	v_mul_f32_e32 v213, 0xbfb8aa3b, v213
	v_mul_f32_e32 v214, 0xbfb8aa3b, v214
	v_mul_f32_e32 v215, 0xbfb8aa3b, v215
	v_exp_f32_e32 v212, v212
	v_exp_f32_e32 v213, v213
	v_exp_f32_e32 v214, v214
	v_exp_f32_e32 v215, v215
	v_add_f32_e32 v212, 1.0, v212
	v_add_f32_e32 v213, 1.0, v213
	v_add_f32_e32 v214, 1.0, v214
	v_add_f32_e32 v215, 1.0, v215
	v_rcp_f32_e32 v212, v212
	v_rcp_f32_e32 v213, v213
	v_rcp_f32_e32 v214, v214
	v_rcp_f32_e32 v215, v215
	v_fma_mixlo_f16 v212, v212, s48, 0
	v_mul_f32_e32 v213, s48, v213
	v_mul_f32_e32 v214, s48, v214
	v_fma_mixlo_f16 v215, v215, s48, 0
	v_cvt_pk_f16_f32 v213, v213, v214
	v_pack_b32_f16 v154, v212, v213
	v_alignbit_b32 v155, v215, v213, 16
	ds_write_b64 v151, v[154:155]
	s_waitcnt lgkmcnt(4)
	global_store_dwordx4 v146, v[236:239], s[66:67]
	global_store_dwordx4 v147, v[240:243], s[66:67]
	v_add_u32_e32 v146, 0x8000, v146
	v_add_u32_e32 v147, 0x8000, v147
	ds_read_b128 v[236:239], v156
	ds_read_b128 v[240:243], v156 offset:1024
	v_pk_add_f32 v[204:205], v[28:29], v[220:221]
	v_pk_add_f32 v[206:207], v[30:31], v[222:223]
	v_mul_f32_e32 v204, 0xbfb8aa3b, v204
	v_mul_f32_e32 v205, 0xbfb8aa3b, v205
	v_mul_f32_e32 v206, 0xbfb8aa3b, v206
	v_mul_f32_e32 v207, 0xbfb8aa3b, v207
	v_exp_f32_e32 v204, v204
	v_exp_f32_e32 v205, v205
	v_exp_f32_e32 v206, v206
	v_exp_f32_e32 v207, v207
	v_add_f32_e32 v204, 1.0, v204
	v_add_f32_e32 v205, 1.0, v205
	v_add_f32_e32 v206, 1.0, v206
	v_add_f32_e32 v207, 1.0, v207
	v_rcp_f32_e32 v204, v204
	v_rcp_f32_e32 v205, v205
	v_rcp_f32_e32 v206, v206
	v_rcp_f32_e32 v207, v207
	v_fma_mixlo_f16 v204, v204, s48, 0
	v_mul_f32_e32 v205, s48, v205
	v_mul_f32_e32 v206, s48, v206
	v_fma_mixlo_f16 v207, v207, s48, 0
	v_cvt_pk_f16_f32 v205, v205, v206
	v_pack_b32_f16 v152, v204, v205
	v_alignbit_b32 v153, v207, v205, 16
	ds_write_b64 v148, v[152:153]
	v_pk_add_f32 v[212:213], v[24:25], v[224:225]
	v_pk_add_f32 v[214:215], v[26:27], v[226:227]
	v_mul_f32_e32 v212, 0xbfb8aa3b, v212
	v_mul_f32_e32 v213, 0xbfb8aa3b, v213
	v_mul_f32_e32 v214, 0xbfb8aa3b, v214
	v_mul_f32_e32 v215, 0xbfb8aa3b, v215
	v_exp_f32_e32 v212, v212
	v_exp_f32_e32 v213, v213
	v_exp_f32_e32 v214, v214
	v_exp_f32_e32 v215, v215
	v_add_f32_e32 v212, 1.0, v212
	v_add_f32_e32 v213, 1.0, v213
	v_add_f32_e32 v214, 1.0, v214
	v_add_f32_e32 v215, 1.0, v215
	v_rcp_f32_e32 v212, v212
	v_rcp_f32_e32 v213, v213
	v_rcp_f32_e32 v214, v214
	v_rcp_f32_e32 v215, v215
	v_fma_mixlo_f16 v212, v212, s48, 0
	v_mul_f32_e32 v213, s48, v213
	v_mul_f32_e32 v214, s48, v214
	v_fma_mixlo_f16 v215, v215, s48, 0
	v_cvt_pk_f16_f32 v213, v213, v214
	v_pack_b32_f16 v154, v212, v213
	v_alignbit_b32 v155, v215, v213, 16
	ds_write_b64 v149, v[154:155]
	v_pk_add_f32 v[204:205], v[20:21], v[228:229]
	v_pk_add_f32 v[206:207], v[22:23], v[230:231]
	v_mul_f32_e32 v204, 0xbfb8aa3b, v204
	v_mul_f32_e32 v205, 0xbfb8aa3b, v205
	v_mul_f32_e32 v206, 0xbfb8aa3b, v206
	v_mul_f32_e32 v207, 0xbfb8aa3b, v207
	v_exp_f32_e32 v204, v204
	v_exp_f32_e32 v205, v205
	v_exp_f32_e32 v206, v206
	v_exp_f32_e32 v207, v207
	v_add_f32_e32 v204, 1.0, v204
	v_add_f32_e32 v205, 1.0, v205
	v_add_f32_e32 v206, 1.0, v206
	v_add_f32_e32 v207, 1.0, v207
	v_rcp_f32_e32 v204, v204
	v_rcp_f32_e32 v205, v205
	v_rcp_f32_e32 v206, v206
	v_rcp_f32_e32 v207, v207
	v_fma_mixlo_f16 v204, v204, s48, 0
	v_mul_f32_e32 v205, s48, v205
	v_mul_f32_e32 v206, s48, v206
	v_fma_mixlo_f16 v207, v207, s48, 0
	v_cvt_pk_f16_f32 v205, v205, v206
	v_pack_b32_f16 v152, v204, v205
	v_alignbit_b32 v153, v207, v205, 16
	ds_write_b64 v150, v[152:153]
	v_pk_add_f32 v[212:213], v[16:17], v[232:233]
	v_pk_add_f32 v[214:215], v[18:19], v[234:235]
	v_mul_f32_e32 v212, 0xbfb8aa3b, v212
	v_mul_f32_e32 v213, 0xbfb8aa3b, v213
	v_mul_f32_e32 v214, 0xbfb8aa3b, v214
	v_mul_f32_e32 v215, 0xbfb8aa3b, v215
	v_exp_f32_e32 v212, v212
	v_exp_f32_e32 v213, v213
	v_exp_f32_e32 v214, v214
	v_exp_f32_e32 v215, v215
	v_add_f32_e32 v212, 1.0, v212
	v_add_f32_e32 v213, 1.0, v213
	v_add_f32_e32 v214, 1.0, v214
	v_add_f32_e32 v215, 1.0, v215
	v_rcp_f32_e32 v212, v212
	v_rcp_f32_e32 v213, v213
	v_rcp_f32_e32 v214, v214
	v_rcp_f32_e32 v215, v215
	v_fma_mixlo_f16 v212, v212, s48, 0
	v_mul_f32_e32 v213, s48, v213
	v_mul_f32_e32 v214, s48, v214
	v_fma_mixlo_f16 v215, v215, s48, 0
	v_cvt_pk_f16_f32 v213, v213, v214
	v_pack_b32_f16 v154, v212, v213
	v_alignbit_b32 v155, v215, v213, 16
	ds_write_b64 v151, v[154:155]
	s_waitcnt lgkmcnt(4)
	global_store_dwordx4 v146, v[236:239], s[66:67]
	global_store_dwordx4 v147, v[240:243], s[66:67]
	v_add_u32_e32 v146, 0x8000, v146
	v_add_u32_e32 v147, 0x8000, v147
	ds_read_b128 v[236:239], v156
	ds_read_b128 v[240:243], v156 offset:1024
	v_pk_add_f32 v[204:205], v[12:13], v[220:221]
	v_pk_add_f32 v[206:207], v[14:15], v[222:223]
	v_mul_f32_e32 v204, 0xbfb8aa3b, v204
	v_mul_f32_e32 v205, 0xbfb8aa3b, v205
	v_mul_f32_e32 v206, 0xbfb8aa3b, v206
	v_mul_f32_e32 v207, 0xbfb8aa3b, v207
	v_exp_f32_e32 v204, v204
	v_exp_f32_e32 v205, v205
	v_exp_f32_e32 v206, v206
	v_exp_f32_e32 v207, v207
	v_add_f32_e32 v204, 1.0, v204
	v_add_f32_e32 v205, 1.0, v205
	v_add_f32_e32 v206, 1.0, v206
	v_add_f32_e32 v207, 1.0, v207
	v_rcp_f32_e32 v204, v204
	v_rcp_f32_e32 v205, v205
	v_rcp_f32_e32 v206, v206
	v_rcp_f32_e32 v207, v207
	v_fma_mixlo_f16 v204, v204, s48, 0
	v_mul_f32_e32 v205, s48, v205
	v_mul_f32_e32 v206, s48, v206
	v_fma_mixlo_f16 v207, v207, s48, 0
	v_cvt_pk_f16_f32 v205, v205, v206
	v_pack_b32_f16 v152, v204, v205
	v_alignbit_b32 v153, v207, v205, 16
	ds_write_b64 v148, v[152:153]
	v_pk_add_f32 v[212:213], v[8:9], v[224:225]
	v_pk_add_f32 v[214:215], v[10:11], v[226:227]
	v_mul_f32_e32 v212, 0xbfb8aa3b, v212
	v_mul_f32_e32 v213, 0xbfb8aa3b, v213
	v_mul_f32_e32 v214, 0xbfb8aa3b, v214
	v_mul_f32_e32 v215, 0xbfb8aa3b, v215
	v_exp_f32_e32 v212, v212
	v_exp_f32_e32 v213, v213
	v_exp_f32_e32 v214, v214
	v_exp_f32_e32 v215, v215
	v_add_f32_e32 v212, 1.0, v212
	v_add_f32_e32 v213, 1.0, v213
	v_add_f32_e32 v214, 1.0, v214
	v_add_f32_e32 v215, 1.0, v215
	v_rcp_f32_e32 v212, v212
	v_rcp_f32_e32 v213, v213
	v_rcp_f32_e32 v214, v214
	v_rcp_f32_e32 v215, v215
	v_fma_mixlo_f16 v212, v212, s48, 0
	v_mul_f32_e32 v213, s48, v213
	v_mul_f32_e32 v214, s48, v214
	v_fma_mixlo_f16 v215, v215, s48, 0
	v_cvt_pk_f16_f32 v213, v213, v214
	v_pack_b32_f16 v154, v212, v213
	v_alignbit_b32 v155, v215, v213, 16
	ds_write_b64 v149, v[154:155]
	v_pk_add_f32 v[204:205], v[4:5], v[228:229]
	v_pk_add_f32 v[206:207], v[6:7], v[230:231]
	v_mul_f32_e32 v204, 0xbfb8aa3b, v204
	v_mul_f32_e32 v205, 0xbfb8aa3b, v205
	v_mul_f32_e32 v206, 0xbfb8aa3b, v206
	v_mul_f32_e32 v207, 0xbfb8aa3b, v207
	v_exp_f32_e32 v204, v204
	v_exp_f32_e32 v205, v205
	v_exp_f32_e32 v206, v206
	v_exp_f32_e32 v207, v207
	v_add_f32_e32 v204, 1.0, v204
	v_add_f32_e32 v205, 1.0, v205
	v_add_f32_e32 v206, 1.0, v206
	v_add_f32_e32 v207, 1.0, v207
	v_rcp_f32_e32 v204, v204
	v_rcp_f32_e32 v205, v205
	v_rcp_f32_e32 v206, v206
	v_rcp_f32_e32 v207, v207
	v_fma_mixlo_f16 v204, v204, s48, 0
	v_mul_f32_e32 v205, s48, v205
	v_mul_f32_e32 v206, s48, v206
	v_fma_mixlo_f16 v207, v207, s48, 0
	v_cvt_pk_f16_f32 v205, v205, v206
	v_pack_b32_f16 v152, v204, v205
	v_alignbit_b32 v153, v207, v205, 16
	ds_write_b64 v150, v[152:153]
	v_pk_add_f32 v[212:213], v[0:1], v[232:233]
	v_pk_add_f32 v[214:215], v[2:3], v[234:235]
	v_mul_f32_e32 v212, 0xbfb8aa3b, v212
	v_mul_f32_e32 v213, 0xbfb8aa3b, v213
	v_mul_f32_e32 v214, 0xbfb8aa3b, v214
	v_mul_f32_e32 v215, 0xbfb8aa3b, v215
	v_exp_f32_e32 v212, v212
	v_exp_f32_e32 v213, v213
	v_exp_f32_e32 v214, v214
	v_exp_f32_e32 v215, v215
	v_add_f32_e32 v212, 1.0, v212
	v_add_f32_e32 v213, 1.0, v213
	v_add_f32_e32 v214, 1.0, v214
	v_add_f32_e32 v215, 1.0, v215
	v_rcp_f32_e32 v212, v212
	v_rcp_f32_e32 v213, v213
	v_rcp_f32_e32 v214, v214
	v_rcp_f32_e32 v215, v215
	v_fma_mixlo_f16 v212, v212, s48, 0
	v_mul_f32_e32 v213, s48, v213
	v_mul_f32_e32 v214, s48, v214
	v_fma_mixlo_f16 v215, v215, s48, 0
	v_cvt_pk_f16_f32 v213, v213, v214
	v_pack_b32_f16 v154, v212, v213
	v_alignbit_b32 v155, v215, v213, 16
	ds_write_b64 v151, v[154:155]
	s_waitcnt lgkmcnt(4)
	global_store_dwordx4 v146, v[236:239], s[66:67]
	global_store_dwordx4 v147, v[240:243], s[66:67]
	v_add_u32_e32 v146, 0x8000, v146
	v_add_u32_e32 v147, 0x8000, v147
	ds_read_b128 v[236:239], v156
	ds_read_b128 v[240:243], v156 offset:1024
	s_waitcnt lgkmcnt(0)
	global_store_dwordx4 v146, v[236:239], s[66:67]
	global_store_dwordx4 v147, v[240:243], s[66:67]
	s_branch .LBB0_261
